# EpiResid epilogues: row sum-of-squares atomics issued together at epilogue end; S5 stage-1 first-direction state store deferred past second-direction loads
# speedup vs baseline: 1.0217x; 1.0008x over previous
.LBB0_443:
	s_lshl_b32 s22, s71, 8
	s_add_i32 s2, s22, 0xffffe000
	s_ashr_i32 s2, s2, 12
	s_add_i32 s2, s2, 1
	v_readlane_b32 s72, v243, 23
	s_cmp_lt_i32 s71, 32
	v_readlane_b32 s73, v243, 24
	s_cselect_b32 s23, 0, s2
	s_mov_b64 s[56:57], s[72:73]
	s_mul_i32 s2, s23, 0x12000
	s_cselect_b32 s20, s56, s54
	s_cselect_b32 s21, s57, s55
	v_readlane_b32 s56, v243, 42
	s_mul_hi_i32 s3, s23, 0x12000
	v_readlane_b32 s57, v243, 43
	s_add_u32 s2, s56, s2
	s_addc_u32 s3, s57, s3
	s_lshl_b32 s33, s70, 8
	v_mov_b32_e32 v193, v173
	v_mov_b32_e32 v194, v175
	s_or_b32 s33, s33, s31
	s_add_i32 s22, s22, s30
	v_lshl_add_u32 v160, v194, 3, s33
	v_ashrrev_i32_e32 v161, 31, v160
	v_lshlrev_b64 v[182:183], 2, v[160:161]
	v_lshl_add_u64 v[72:73], s[2:3], 0, v[182:183]
	s_mov_b64 s[2:3], 0x4000
	v_lshl_add_u64 v[162:163], v[72:73], 0, s[2:3]
	s_lshl_b32 s2, s23, 11
	s_ashr_i32 s3, s2, 31
	s_lshl_b64 s[2:3], s[2:3], 2
	s_add_u32 s2, s52, s2
	s_addc_u32 s3, s53, s3
	v_lshl_add_u64 v[164:165], s[2:3], 0, v[182:183]
	s_movk_i32 s2, 0x4000
	v_add_co_u32_e32 v72, vcc, s2, v72
	v_readlane_b32 s74, v243, 25
	s_nop 0
	v_addc_co_u32_e32 v73, vcc, 0, v73, vcc
	global_load_dwordx4 v[72:75], v[72:73], off
	s_nop 0
	global_load_dwordx4 v[76:79], v[162:163], off offset:16
	global_load_dwordx4 v[88:91], v[164:165], off offset:16
	global_load_dwordx4 v[92:95], v[164:165], off
	v_cmp_eq_u32_e32 vcc, 0, v194
	v_readlane_b32 s75, v243, 26
	v_readlane_b32 s76, v243, 27
	v_readlane_b32 s77, v243, 28
	v_readlane_b32 s78, v243, 29
	v_readlane_b32 s79, v243, 30
	v_readlane_b32 s80, v243, 31
	v_readlane_b32 s81, v243, 32
	v_readlane_b32 s82, v243, 33
	v_readlane_b32 s83, v243, 34
	v_readlane_b32 s84, v243, 35
	v_readlane_b32 s85, v243, 36
	v_readlane_b32 s86, v243, 37
	v_readlane_b32 s87, v243, 38
	s_waitcnt vmcnt(0)
	v_pk_mul_f32 v[170:171], v[74:75], 0.5 op_sel_hi:[1,0]
	v_pk_mul_f32 v[176:177], v[72:73], 0.5 op_sel_hi:[1,0]
	global_load_dwordx4 v[184:187], v[162:163], off offset:528
	global_load_dwordx4 v[72:75], v[162:163], off offset:512
	v_pk_mul_f32 v[178:179], v[78:79], 0.5 op_sel_hi:[1,0]
	v_pk_mul_f32 v[180:181], v[76:77], 0.5 op_sel_hi:[1,0]
	s_waitcnt vmcnt(1)
	v_pk_mul_f32 v[162:163], v[186:187], 0.5 op_sel_hi:[1,0]
	s_waitcnt vmcnt(0)
	v_pk_mul_f32 v[166:167], v[74:75], 0.5 op_sel_hi:[1,0]
	v_pk_mul_f32 v[168:169], v[72:73], 0.5 op_sel_hi:[1,0]
	global_load_dwordx4 v[72:75], v[164:165], off offset:528
	global_load_dwordx4 v[76:79], v[164:165], off offset:512
	v_pk_mul_f32 v[164:165], v[184:185], 0.5 op_sel_hi:[1,0]
	v_add_u32_e32 v184, s22, v193
	v_ashrrev_i32_e32 v185, 31, v184
	v_lshlrev_b64 v[204:205], 13, v[184:185]
	v_lshl_add_u64 v[186:187], s[20:21], 0, v[204:205]
	v_lshlrev_b64 v[194:195], 12, v[184:185]
	v_lshl_add_u64 v[186:187], v[186:187], 0, v[182:183]
	v_lshl_add_u64 v[206:207], s[38:39], 0, v[194:195]
	global_load_dwordx4 v[194:197], v[186:187], off offset:16
	global_load_dwordx4 v[200:203], v[186:187], off
	s_waitcnt vmcnt(1)
	v_pk_fma_f32 v[138:139], v[138:139], v[178:179], v[196:197]
	s_waitcnt vmcnt(0)
	v_pk_fma_f32 v[142:143], v[142:143], v[170:171], v[202:203]
	v_pk_fma_f32 v[140:141], v[140:141], v[176:177], v[200:201]
	v_mul_f32_e32 v196, v143, v143
	v_mul_f32_e32 v193, v141, v141
	v_pk_fma_f32 v[136:137], v[136:137], v[180:181], v[194:195]
	v_fmac_f32_e32 v193, v140, v140
	v_fmac_f32_e32 v196, v142, v142
	v_add_f32_e32 v193, v193, v196
	v_mul_f32_e32 v196, v137, v137
	v_mul_f32_e32 v197, v139, v139
	v_lshl_add_u64 v[194:195], s[90:91], 0, v[204:205]
	v_fmac_f32_e32 v196, v136, v136
	v_fmac_f32_e32 v197, v138, v138
	v_lshl_add_u64 v[194:195], v[194:195], 0, v[182:183]
	v_add_f32_e32 v196, v196, v197
	global_store_dwordx4 v[194:195], v[140:143], off
	global_store_dwordx4 v[194:195], v[136:139], off offset:16
	v_add_f32_e32 v193, v193, v196
	v_pk_mul_f32 v[196:197], v[90:91], v[138:139]
	v_pk_mul_f32 v[138:139], v[88:89], v[136:137]
	v_pk_mul_f32 v[142:143], v[94:95], v[142:143]
	v_pk_mul_f32 v[140:141], v[92:93], v[140:141]
	s_nop 0
	v_cvt_pk_bf16_f32 v136, v140, v141
	v_cvt_pk_bf16_f32 v137, v142, v143
	v_cvt_pk_bf16_f32 v138, v138, v139
	v_cvt_pk_bf16_f32 v139, v196, v197
	v_lshl_add_u64 v[196:197], v[160:161], 1, v[206:207]
	global_store_dwordx4 v[196:197], v[136:139], off
	global_load_dwordx4 v[136:139], v[186:187], off offset:528
	s_nop 0
	global_load_dwordx4 v[140:143], v[186:187], off offset:512
	s_waitcnt vmcnt(1)
	v_pk_fma_f32 v[128:129], v[128:129], v[164:165], v[136:137]
	s_waitcnt vmcnt(0)
	v_pk_fma_f32 v[134:135], v[134:135], v[166:167], v[142:143]
	v_pk_fma_f32 v[132:133], v[132:133], v[168:169], v[140:141]
	v_mul_f32_e32 v137, v135, v135
	v_mul_f32_e32 v136, v133, v133
	v_pk_fma_f32 v[130:131], v[130:131], v[162:163], v[138:139]
	v_fmac_f32_e32 v136, v132, v132
	v_fmac_f32_e32 v137, v134, v134
	v_add_f32_e32 v136, v136, v137
	v_mul_f32_e32 v137, v129, v129
	v_mul_f32_e32 v138, v131, v131
	v_fmac_f32_e32 v137, v128, v128
	v_fmac_f32_e32 v138, v130, v130
	v_add_f32_e32 v137, v137, v138
	v_add_f32_e32 v136, v136, v137
	global_store_dwordx4 v[194:195], v[132:135], off offset:512
	global_store_dwordx4 v[194:195], v[128:131], off offset:528
	v_add_f32_e32 v138, v193, v136
	v_pk_mul_f32 v[134:135], v[78:79], v[134:135]
	v_pk_mul_f32 v[132:133], v[76:77], v[132:133]
	v_pk_mul_f32 v[136:137], v[74:75], v[130:131]
	v_pk_mul_f32 v[130:131], v[72:73], v[128:129]
	v_cvt_pk_bf16_f32 v128, v132, v133
	v_cvt_pk_bf16_f32 v129, v134, v135
	s_nop 0
	v_cvt_pk_bf16_f32 v130, v130, v131
	v_cvt_pk_bf16_f32 v131, v136, v137
	global_store_dwordx4 v[196:197], v[128:131], off offset:256
	s_nop 1
	v_and_b32_e32 v129, 64, v192
	v_xor_b32_e32 v128, 16, v192
	v_add_u32_e32 v129, 64, v129
	v_cmp_lt_i32_e64 s[2:3], v128, v129
	v_xor_b32_e32 v131, 32, v192
	s_nop 0
	v_cndmask_b32_e64 v128, v192, v128, s[2:3]
	v_lshlrev_b32_e32 v130, 2, v128
	ds_bpermute_b32 v128, v130, v138
	v_cmp_lt_i32_e64 s[2:3], v131, v129
	s_waitcnt lgkmcnt(0)
	v_add_f32_e32 v128, v138, v128
	v_cndmask_b32_e64 v129, v192, v131, s[2:3]
	v_lshlrev_b32_e32 v131, 2, v129
	ds_bpermute_b32 v129, v131, v128
	s_and_saveexec_b64 s[2:3], vcc
	s_cbranch_execz .LBB0_445
	v_lshl_add_u64 v[132:133], v[184:185], 2, s[10:11]
	s_waitcnt lgkmcnt(0)
	v_add_f32_e32 v128, v128, v129
	v_mov_b32_e32 v230, v128
	v_mov_b32_e32 v238, v132
	v_mov_b32_e32 v239, v133
.LBB0_445:
	s_or_b64 exec, exec, s[2:3]
	v_add_u32_e32 v128, 16, v184
	s_waitcnt lgkmcnt(0)
	v_ashrrev_i32_e32 v129, 31, v128
	v_lshlrev_b64 v[140:141], 13, v[128:129]
	v_lshl_add_u64 v[132:133], s[20:21], 0, v[140:141]
	v_lshl_add_u64 v[142:143], v[132:133], 0, v[182:183]
	global_load_dwordx4 v[132:135], v[142:143], off
	global_load_dwordx4 v[136:139], v[142:143], off offset:16
	v_lshlrev_b64 v[186:187], 12, v[128:129]
	v_lshl_add_u64 v[186:187], s[38:39], 0, v[186:187]
	v_lshl_add_u64 v[140:141], s[90:91], 0, v[140:141]
	v_lshl_add_u64 v[140:141], v[140:141], 0, v[182:183]
	v_lshl_add_u64 v[186:187], v[160:161], 1, v[186:187]
	s_waitcnt vmcnt(1)
	v_pk_fma_f32 v[126:127], v[126:127], v[170:171], v[134:135]
	v_pk_fma_f32 v[124:125], v[124:125], v[176:177], v[132:133]
	s_waitcnt vmcnt(0)
	v_pk_fma_f32 v[122:123], v[122:123], v[178:179], v[138:139]
	v_pk_fma_f32 v[120:121], v[120:121], v[180:181], v[136:137]
	v_pk_mul_f32 v[134:135], v[94:95], v[126:127]
	v_pk_mul_f32 v[132:133], v[92:93], v[124:125]
	global_store_dwordx4 v[140:141], v[124:127], off
	global_store_dwordx4 v[140:141], v[120:123], off offset:16
	v_pk_mul_f32 v[136:137], v[90:91], v[122:123]
	v_pk_mul_f32 v[138:139], v[88:89], v[120:121]
	v_cvt_pk_bf16_f32 v132, v132, v133
	v_cvt_pk_bf16_f32 v133, v134, v135
	v_mul_f32_e32 v125, v125, v125
	v_cvt_pk_bf16_f32 v134, v138, v139
	v_cvt_pk_bf16_f32 v135, v136, v137
	global_store_dwordx4 v[186:187], v[132:135], off
	global_load_dwordx4 v[132:135], v[142:143], off offset:512
	s_nop 0
	global_load_dwordx4 v[136:139], v[142:143], off offset:528
	v_mul_f32_e32 v127, v127, v127
	v_mul_f32_e32 v121, v121, v121
	v_mul_f32_e32 v123, v123, v123
	v_fmac_f32_e32 v125, v124, v124
	v_fmac_f32_e32 v127, v126, v126
	v_fmac_f32_e32 v121, v120, v120
	v_fmac_f32_e32 v123, v122, v122
	v_add_f32_e32 v120, v125, v127
	v_add_f32_e32 v121, v121, v123
	v_add_f32_e32 v120, v120, v121
	s_waitcnt vmcnt(1)
	v_pk_fma_f32 v[118:119], v[118:119], v[166:167], v[134:135]
	v_pk_fma_f32 v[116:117], v[116:117], v[168:169], v[132:133]
	s_waitcnt vmcnt(0)
	v_pk_fma_f32 v[114:115], v[114:115], v[162:163], v[138:139]
	v_pk_fma_f32 v[112:113], v[112:113], v[164:165], v[136:137]
	v_mul_f32_e32 v121, v117, v117
	v_mul_f32_e32 v122, v119, v119
	v_mul_f32_e32 v123, v113, v113
	v_mul_f32_e32 v124, v115, v115
	v_fmac_f32_e32 v121, v116, v116
	v_fmac_f32_e32 v122, v118, v118
	v_fmac_f32_e32 v123, v112, v112
	v_fmac_f32_e32 v124, v114, v114
	v_add_f32_e32 v121, v121, v122
	v_add_f32_e32 v122, v123, v124
	v_add_f32_e32 v121, v121, v122
	v_add_f32_e32 v124, v120, v121
	ds_bpermute_b32 v125, v130, v124
	global_store_dwordx4 v[140:141], v[116:119], off offset:512
	global_store_dwordx4 v[140:141], v[112:115], off offset:528
	v_pk_mul_f32 v[122:123], v[72:73], v[112:113]
	v_pk_mul_f32 v[116:117], v[76:77], v[116:117]
	v_pk_mul_f32 v[118:119], v[78:79], v[118:119]
	s_waitcnt lgkmcnt(0)
	v_add_f32_e32 v112, v124, v125
	ds_bpermute_b32 v113, v131, v112
	v_pk_mul_f32 v[120:121], v[74:75], v[114:115]
	v_cvt_pk_bf16_f32 v114, v116, v117
	v_cvt_pk_bf16_f32 v115, v118, v119
	v_cvt_pk_bf16_f32 v116, v122, v123
	s_nop 0
	v_cvt_pk_bf16_f32 v117, v120, v121
	global_store_dwordx4 v[186:187], v[114:117], off offset:256
	s_and_saveexec_b64 s[2:3], vcc
	s_cbranch_execz .LBB0_447
	v_lshl_add_u64 v[114:115], v[128:129], 2, s[10:11]
	s_waitcnt lgkmcnt(0)
	v_add_f32_e32 v112, v112, v113
	v_mov_b32_e32 v231, v112
.LBB0_447:
	s_or_b64 exec, exec, s[2:3]
	v_add_u32_e32 v112, 32, v184
	s_waitcnt lgkmcnt(0)
	v_ashrrev_i32_e32 v113, 31, v112
	v_lshlrev_b64 v[122:123], 13, v[112:113]
	v_lshl_add_u64 v[114:115], s[20:21], 0, v[122:123]
	v_lshl_add_u64 v[124:125], v[114:115], 0, v[182:183]
	global_load_dwordx4 v[114:117], v[124:125], off
	global_load_dwordx4 v[118:121], v[124:125], off offset:16
	v_lshlrev_b64 v[126:127], 12, v[112:113]
	v_lshl_add_u64 v[126:127], s[38:39], 0, v[126:127]
	v_lshl_add_u64 v[122:123], s[90:91], 0, v[122:123]
	v_lshl_add_u64 v[122:123], v[122:123], 0, v[182:183]
	v_lshl_add_u64 v[126:127], v[160:161], 1, v[126:127]
	s_waitcnt vmcnt(1)
	v_pk_fma_f32 v[110:111], v[110:111], v[170:171], v[116:117]
	v_pk_fma_f32 v[108:109], v[108:109], v[176:177], v[114:115]
	s_waitcnt vmcnt(0)
	v_pk_fma_f32 v[106:107], v[106:107], v[178:179], v[120:121]
	v_pk_fma_f32 v[104:105], v[104:105], v[180:181], v[118:119]
	v_pk_mul_f32 v[116:117], v[94:95], v[110:111]
	v_pk_mul_f32 v[114:115], v[92:93], v[108:109]
	global_store_dwordx4 v[122:123], v[108:111], off
	global_store_dwordx4 v[122:123], v[104:107], off offset:16
	v_pk_mul_f32 v[118:119], v[90:91], v[106:107]
	v_pk_mul_f32 v[120:121], v[88:89], v[104:105]
	v_cvt_pk_bf16_f32 v114, v114, v115
	v_cvt_pk_bf16_f32 v115, v116, v117
	v_mul_f32_e32 v109, v109, v109
	v_cvt_pk_bf16_f32 v116, v120, v121
	v_cvt_pk_bf16_f32 v117, v118, v119
	global_store_dwordx4 v[126:127], v[114:117], off
	global_load_dwordx4 v[114:117], v[124:125], off offset:512
	s_nop 0
	global_load_dwordx4 v[118:121], v[124:125], off offset:528
	v_mul_f32_e32 v111, v111, v111
	v_mul_f32_e32 v105, v105, v105
	v_mul_f32_e32 v107, v107, v107
	v_fmac_f32_e32 v109, v108, v108
	v_fmac_f32_e32 v111, v110, v110
	v_fmac_f32_e32 v105, v104, v104
	v_fmac_f32_e32 v107, v106, v106
	v_add_f32_e32 v104, v109, v111
	v_add_f32_e32 v105, v105, v107
	v_add_f32_e32 v104, v104, v105
	s_waitcnt vmcnt(1)
	v_pk_fma_f32 v[102:103], v[102:103], v[166:167], v[116:117]
	v_pk_fma_f32 v[100:101], v[100:101], v[168:169], v[114:115]
	s_waitcnt vmcnt(0)
	v_pk_fma_f32 v[98:99], v[98:99], v[162:163], v[120:121]
	v_pk_fma_f32 v[96:97], v[96:97], v[164:165], v[118:119]
	v_mul_f32_e32 v105, v101, v101
	v_mul_f32_e32 v106, v103, v103
	v_mul_f32_e32 v107, v97, v97
	v_mul_f32_e32 v108, v99, v99
	v_fmac_f32_e32 v105, v100, v100
	v_fmac_f32_e32 v106, v102, v102
	v_fmac_f32_e32 v107, v96, v96
	v_fmac_f32_e32 v108, v98, v98
	v_add_f32_e32 v105, v105, v106
	v_add_f32_e32 v106, v107, v108
	v_add_f32_e32 v105, v105, v106
	v_add_f32_e32 v108, v104, v105
	ds_bpermute_b32 v109, v130, v108
	global_store_dwordx4 v[122:123], v[100:103], off offset:512
	global_store_dwordx4 v[122:123], v[96:99], off offset:528
	v_pk_mul_f32 v[106:107], v[72:73], v[96:97]
	v_pk_mul_f32 v[100:101], v[76:77], v[100:101]
	v_pk_mul_f32 v[102:103], v[78:79], v[102:103]
	s_waitcnt lgkmcnt(0)
	v_add_f32_e32 v96, v108, v109
	ds_bpermute_b32 v97, v131, v96
	v_pk_mul_f32 v[104:105], v[74:75], v[98:99]
	v_cvt_pk_bf16_f32 v98, v100, v101
	v_cvt_pk_bf16_f32 v99, v102, v103
	v_cvt_pk_bf16_f32 v100, v106, v107
	s_nop 0
	v_cvt_pk_bf16_f32 v101, v104, v105
	global_store_dwordx4 v[126:127], v[98:101], off offset:256
	s_and_saveexec_b64 s[2:3], vcc
	s_cbranch_execz .LBB0_449
	v_lshl_add_u64 v[98:99], v[112:113], 2, s[10:11]
	s_waitcnt lgkmcnt(0)
	v_add_f32_e32 v96, v96, v97
	v_mov_b32_e32 v232, v96
.LBB0_449:
	s_or_b64 exec, exec, s[2:3]
	v_add_u32_e32 v96, 48, v184
	s_waitcnt lgkmcnt(0)
	v_ashrrev_i32_e32 v97, 31, v96
	v_lshlrev_b64 v[106:107], 13, v[96:97]
	v_lshl_add_u64 v[98:99], s[20:21], 0, v[106:107]
	v_lshl_add_u64 v[108:109], v[98:99], 0, v[182:183]
	global_load_dwordx4 v[98:101], v[108:109], off
	global_load_dwordx4 v[102:105], v[108:109], off offset:16
	v_lshlrev_b64 v[110:111], 12, v[96:97]
	v_lshl_add_u64 v[110:111], s[38:39], 0, v[110:111]
	v_lshl_add_u64 v[106:107], s[90:91], 0, v[106:107]
	v_lshl_add_u64 v[106:107], v[106:107], 0, v[182:183]
	v_lshl_add_u64 v[110:111], v[160:161], 1, v[110:111]
	s_waitcnt vmcnt(1)
	v_pk_fma_f32 v[86:87], v[86:87], v[170:171], v[100:101]
	v_pk_fma_f32 v[84:85], v[84:85], v[176:177], v[98:99]
	s_waitcnt vmcnt(0)
	v_pk_fma_f32 v[82:83], v[82:83], v[178:179], v[104:105]
	v_pk_fma_f32 v[80:81], v[80:81], v[180:181], v[102:103]
	v_pk_mul_f32 v[100:101], v[94:95], v[86:87]
	v_pk_mul_f32 v[98:99], v[92:93], v[84:85]
	global_store_dwordx4 v[106:107], v[84:87], off
	global_store_dwordx4 v[106:107], v[80:83], off offset:16
	v_pk_mul_f32 v[102:103], v[90:91], v[82:83]
	v_pk_mul_f32 v[104:105], v[88:89], v[80:81]
	v_cvt_pk_bf16_f32 v98, v98, v99
	v_cvt_pk_bf16_f32 v99, v100, v101
	v_mul_f32_e32 v85, v85, v85
	v_cvt_pk_bf16_f32 v100, v104, v105
	v_cvt_pk_bf16_f32 v101, v102, v103
	global_store_dwordx4 v[110:111], v[98:101], off
	global_load_dwordx4 v[98:101], v[108:109], off offset:512
	s_nop 0
	global_load_dwordx4 v[102:105], v[108:109], off offset:528
	v_mul_f32_e32 v87, v87, v87
	v_mul_f32_e32 v81, v81, v81
	v_mul_f32_e32 v83, v83, v83
	v_fmac_f32_e32 v85, v84, v84
	v_fmac_f32_e32 v87, v86, v86
	v_fmac_f32_e32 v81, v80, v80
	v_fmac_f32_e32 v83, v82, v82
	v_add_f32_e32 v80, v85, v87
	v_add_f32_e32 v81, v81, v83
	v_add_f32_e32 v80, v80, v81
	s_waitcnt vmcnt(1)
	v_pk_fma_f32 v[70:71], v[70:71], v[166:167], v[100:101]
	v_pk_fma_f32 v[68:69], v[68:69], v[168:169], v[98:99]
	s_waitcnt vmcnt(0)
	v_pk_fma_f32 v[66:67], v[66:67], v[162:163], v[104:105]
	v_pk_fma_f32 v[64:65], v[64:65], v[164:165], v[102:103]
	v_mul_f32_e32 v81, v69, v69
	v_mul_f32_e32 v82, v71, v71
	v_mul_f32_e32 v83, v65, v65
	v_mul_f32_e32 v84, v67, v67
	v_fmac_f32_e32 v81, v68, v68
	v_fmac_f32_e32 v82, v70, v70
	v_fmac_f32_e32 v83, v64, v64
	v_fmac_f32_e32 v84, v66, v66
	v_add_f32_e32 v81, v81, v82
	v_add_f32_e32 v82, v83, v84
	v_add_f32_e32 v81, v81, v82
	v_add_f32_e32 v84, v80, v81
	ds_bpermute_b32 v85, v130, v84
	global_store_dwordx4 v[106:107], v[68:71], off offset:512
	global_store_dwordx4 v[106:107], v[64:67], off offset:528
	v_pk_mul_f32 v[82:83], v[72:73], v[64:65]
	v_pk_mul_f32 v[68:69], v[76:77], v[68:69]
	v_pk_mul_f32 v[70:71], v[78:79], v[70:71]
	s_waitcnt lgkmcnt(0)
	v_add_f32_e32 v64, v84, v85
	ds_bpermute_b32 v65, v131, v64
	v_pk_mul_f32 v[80:81], v[74:75], v[66:67]
	v_cvt_pk_bf16_f32 v66, v68, v69
	v_cvt_pk_bf16_f32 v67, v70, v71
	v_cvt_pk_bf16_f32 v68, v82, v83
	s_nop 0
	v_cvt_pk_bf16_f32 v69, v80, v81
	global_store_dwordx4 v[110:111], v[66:69], off offset:256
	s_and_saveexec_b64 s[2:3], vcc
	s_cbranch_execz .LBB0_451
	v_lshl_add_u64 v[66:67], v[96:97], 2, s[10:11]
	s_waitcnt lgkmcnt(0)
	v_add_f32_e32 v64, v64, v65
	v_mov_b32_e32 v233, v64
.LBB0_451:
	s_or_b64 exec, exec, s[2:3]
	v_add_u32_e32 v64, 0x80, v184
	s_waitcnt lgkmcnt(0)
	v_ashrrev_i32_e32 v65, 31, v64
	v_lshlrev_b64 v[70:71], 13, v[64:65]
	v_lshl_add_u64 v[66:67], s[20:21], 0, v[70:71]
	v_lshl_add_u64 v[84:85], v[66:67], 0, v[182:183]
	global_load_dwordx4 v[66:69], v[84:85], off
	global_load_dwordx4 v[80:83], v[84:85], off offset:16
	v_lshlrev_b64 v[86:87], 12, v[64:65]
	v_lshl_add_u64 v[86:87], s[38:39], 0, v[86:87]
	v_lshl_add_u64 v[70:71], s[90:91], 0, v[70:71]
	v_lshl_add_u64 v[70:71], v[70:71], 0, v[182:183]
	v_lshl_add_u64 v[86:87], v[160:161], 1, v[86:87]
	s_waitcnt vmcnt(1)
	v_pk_fma_f32 v[62:63], v[62:63], v[170:171], v[68:69]
	v_pk_fma_f32 v[60:61], v[60:61], v[176:177], v[66:67]
	s_waitcnt vmcnt(0)
	v_pk_fma_f32 v[58:59], v[58:59], v[178:179], v[82:83]
	v_pk_fma_f32 v[56:57], v[56:57], v[180:181], v[80:81]
	v_pk_mul_f32 v[68:69], v[94:95], v[62:63]
	v_pk_mul_f32 v[66:67], v[92:93], v[60:61]
	global_store_dwordx4 v[70:71], v[60:63], off
	global_store_dwordx4 v[70:71], v[56:59], off offset:16
	v_pk_mul_f32 v[80:81], v[90:91], v[58:59]
	v_pk_mul_f32 v[82:83], v[88:89], v[56:57]
	v_cvt_pk_bf16_f32 v66, v66, v67
	v_cvt_pk_bf16_f32 v67, v68, v69
	v_mul_f32_e32 v61, v61, v61
	v_cvt_pk_bf16_f32 v68, v82, v83
	v_cvt_pk_bf16_f32 v69, v80, v81
	global_store_dwordx4 v[86:87], v[66:69], off
	global_load_dwordx4 v[66:69], v[84:85], off offset:512
	s_nop 0
	global_load_dwordx4 v[80:83], v[84:85], off offset:528
	v_mul_f32_e32 v63, v63, v63
	v_mul_f32_e32 v57, v57, v57
	v_mul_f32_e32 v59, v59, v59
	v_fmac_f32_e32 v61, v60, v60
	v_fmac_f32_e32 v63, v62, v62
	v_fmac_f32_e32 v57, v56, v56
	v_fmac_f32_e32 v59, v58, v58
	v_add_f32_e32 v56, v61, v63
	v_add_f32_e32 v57, v57, v59
	v_add_f32_e32 v56, v56, v57
	s_waitcnt vmcnt(1)
	v_pk_fma_f32 v[54:55], v[54:55], v[166:167], v[68:69]
	v_pk_fma_f32 v[52:53], v[52:53], v[168:169], v[66:67]
	s_waitcnt vmcnt(0)
	v_pk_fma_f32 v[50:51], v[50:51], v[162:163], v[82:83]
	v_pk_fma_f32 v[48:49], v[48:49], v[164:165], v[80:81]
	v_mul_f32_e32 v57, v53, v53
	v_mul_f32_e32 v58, v55, v55
	v_mul_f32_e32 v59, v49, v49
	v_mul_f32_e32 v60, v51, v51
	v_fmac_f32_e32 v57, v52, v52
	v_fmac_f32_e32 v58, v54, v54
	v_fmac_f32_e32 v59, v48, v48
	v_fmac_f32_e32 v60, v50, v50
	v_add_f32_e32 v57, v57, v58
	v_add_f32_e32 v58, v59, v60
	v_add_f32_e32 v57, v57, v58
	v_add_f32_e32 v60, v56, v57
	ds_bpermute_b32 v61, v130, v60
	global_store_dwordx4 v[70:71], v[52:55], off offset:512
	global_store_dwordx4 v[70:71], v[48:51], off offset:528
	v_pk_mul_f32 v[58:59], v[72:73], v[48:49]
	v_pk_mul_f32 v[52:53], v[76:77], v[52:53]
	v_pk_mul_f32 v[54:55], v[78:79], v[54:55]
	s_waitcnt lgkmcnt(0)
	v_add_f32_e32 v48, v60, v61
	ds_bpermute_b32 v49, v131, v48
	v_pk_mul_f32 v[56:57], v[74:75], v[50:51]
	v_cvt_pk_bf16_f32 v50, v52, v53
	v_cvt_pk_bf16_f32 v51, v54, v55
	v_cvt_pk_bf16_f32 v52, v58, v59
	s_nop 0
	v_cvt_pk_bf16_f32 v53, v56, v57
	global_store_dwordx4 v[86:87], v[50:53], off offset:256
	s_and_saveexec_b64 s[2:3], vcc
	s_cbranch_execz .LBB0_453
	v_lshl_add_u64 v[50:51], v[64:65], 2, s[10:11]
	s_waitcnt lgkmcnt(0)
	v_add_f32_e32 v48, v48, v49
	v_mov_b32_e32 v234, v48
.LBB0_453:
	s_or_b64 exec, exec, s[2:3]
	v_add_u32_e32 v48, 0x90, v184
	s_waitcnt lgkmcnt(0)
	v_ashrrev_i32_e32 v49, 31, v48
	v_lshlrev_b64 v[58:59], 13, v[48:49]
	v_lshl_add_u64 v[50:51], s[20:21], 0, v[58:59]
	v_lshl_add_u64 v[60:61], v[50:51], 0, v[182:183]
	global_load_dwordx4 v[50:53], v[60:61], off
	global_load_dwordx4 v[54:57], v[60:61], off offset:16
	v_lshlrev_b64 v[62:63], 12, v[48:49]
	v_lshl_add_u64 v[62:63], s[38:39], 0, v[62:63]
	v_lshl_add_u64 v[58:59], s[90:91], 0, v[58:59]
	v_lshl_add_u64 v[58:59], v[58:59], 0, v[182:183]
	v_lshl_add_u64 v[62:63], v[160:161], 1, v[62:63]
	s_waitcnt vmcnt(1)
	v_pk_fma_f32 v[46:47], v[46:47], v[170:171], v[52:53]
	v_pk_fma_f32 v[44:45], v[44:45], v[176:177], v[50:51]
	s_waitcnt vmcnt(0)
	v_pk_fma_f32 v[42:43], v[42:43], v[178:179], v[56:57]
	v_pk_fma_f32 v[40:41], v[40:41], v[180:181], v[54:55]
	v_pk_mul_f32 v[52:53], v[94:95], v[46:47]
	v_pk_mul_f32 v[50:51], v[92:93], v[44:45]
	global_store_dwordx4 v[58:59], v[44:47], off
	global_store_dwordx4 v[58:59], v[40:43], off offset:16
	v_pk_mul_f32 v[54:55], v[90:91], v[42:43]
	v_pk_mul_f32 v[56:57], v[88:89], v[40:41]
	v_cvt_pk_bf16_f32 v50, v50, v51
	v_cvt_pk_bf16_f32 v51, v52, v53
	v_mul_f32_e32 v45, v45, v45
	v_cvt_pk_bf16_f32 v52, v56, v57
	v_cvt_pk_bf16_f32 v53, v54, v55
	global_store_dwordx4 v[62:63], v[50:53], off
	global_load_dwordx4 v[50:53], v[60:61], off offset:512
	s_nop 0
	global_load_dwordx4 v[54:57], v[60:61], off offset:528
	v_mul_f32_e32 v47, v47, v47
	v_mul_f32_e32 v41, v41, v41
	v_mul_f32_e32 v43, v43, v43
	v_fmac_f32_e32 v45, v44, v44
	v_fmac_f32_e32 v47, v46, v46
	v_fmac_f32_e32 v41, v40, v40
	v_fmac_f32_e32 v43, v42, v42
	v_add_f32_e32 v40, v45, v47
	v_add_f32_e32 v41, v41, v43
	v_add_f32_e32 v40, v40, v41
	s_waitcnt vmcnt(1)
	v_pk_fma_f32 v[38:39], v[38:39], v[166:167], v[52:53]
	v_pk_fma_f32 v[36:37], v[36:37], v[168:169], v[50:51]
	s_waitcnt vmcnt(0)
	v_pk_fma_f32 v[34:35], v[34:35], v[162:163], v[56:57]
	v_pk_fma_f32 v[32:33], v[32:33], v[164:165], v[54:55]
	v_mul_f32_e32 v41, v37, v37
	v_mul_f32_e32 v42, v39, v39
	v_mul_f32_e32 v43, v33, v33
	v_mul_f32_e32 v44, v35, v35
	v_fmac_f32_e32 v41, v36, v36
	v_fmac_f32_e32 v42, v38, v38
	v_fmac_f32_e32 v43, v32, v32
	v_fmac_f32_e32 v44, v34, v34
	v_add_f32_e32 v41, v41, v42
	v_add_f32_e32 v42, v43, v44
	v_add_f32_e32 v41, v41, v42
	v_add_f32_e32 v44, v40, v41
	ds_bpermute_b32 v45, v130, v44
	global_store_dwordx4 v[58:59], v[36:39], off offset:512
	global_store_dwordx4 v[58:59], v[32:35], off offset:528
	v_pk_mul_f32 v[42:43], v[72:73], v[32:33]
	v_pk_mul_f32 v[36:37], v[76:77], v[36:37]
	v_pk_mul_f32 v[38:39], v[78:79], v[38:39]
	s_waitcnt lgkmcnt(0)
	v_add_f32_e32 v32, v44, v45
	ds_bpermute_b32 v33, v131, v32
	v_pk_mul_f32 v[40:41], v[74:75], v[34:35]
	v_cvt_pk_bf16_f32 v34, v36, v37
	v_cvt_pk_bf16_f32 v35, v38, v39
	v_cvt_pk_bf16_f32 v36, v42, v43
	s_nop 0
	v_cvt_pk_bf16_f32 v37, v40, v41
	global_store_dwordx4 v[62:63], v[34:37], off offset:256
	s_and_saveexec_b64 s[2:3], vcc
	s_cbranch_execz .LBB0_455
	v_lshl_add_u64 v[34:35], v[48:49], 2, s[10:11]
	s_waitcnt lgkmcnt(0)
	v_add_f32_e32 v32, v32, v33
	v_mov_b32_e32 v235, v32
.LBB0_455:
	s_or_b64 exec, exec, s[2:3]
	v_add_u32_e32 v32, 0xa0, v184
	s_waitcnt lgkmcnt(0)
	v_ashrrev_i32_e32 v33, 31, v32
	v_lshlrev_b64 v[42:43], 13, v[32:33]
	v_lshl_add_u64 v[34:35], s[20:21], 0, v[42:43]
	v_lshl_add_u64 v[44:45], v[34:35], 0, v[182:183]
	global_load_dwordx4 v[34:37], v[44:45], off
	global_load_dwordx4 v[38:41], v[44:45], off offset:16
	v_lshlrev_b64 v[46:47], 12, v[32:33]
	v_lshl_add_u64 v[46:47], s[38:39], 0, v[46:47]
	v_lshl_add_u64 v[42:43], s[90:91], 0, v[42:43]
	v_lshl_add_u64 v[42:43], v[42:43], 0, v[182:183]
	v_lshl_add_u64 v[46:47], v[160:161], 1, v[46:47]
	s_waitcnt vmcnt(1)
	v_pk_fma_f32 v[30:31], v[30:31], v[170:171], v[36:37]
	v_pk_fma_f32 v[28:29], v[28:29], v[176:177], v[34:35]
	s_waitcnt vmcnt(0)
	v_pk_fma_f32 v[26:27], v[26:27], v[178:179], v[40:41]
	v_pk_fma_f32 v[24:25], v[24:25], v[180:181], v[38:39]
	v_pk_mul_f32 v[36:37], v[94:95], v[30:31]
	v_pk_mul_f32 v[34:35], v[92:93], v[28:29]
	global_store_dwordx4 v[42:43], v[28:31], off
	global_store_dwordx4 v[42:43], v[24:27], off offset:16
	v_pk_mul_f32 v[38:39], v[90:91], v[26:27]
	v_pk_mul_f32 v[40:41], v[88:89], v[24:25]
	v_cvt_pk_bf16_f32 v34, v34, v35
	v_cvt_pk_bf16_f32 v35, v36, v37
	v_mul_f32_e32 v29, v29, v29
	v_cvt_pk_bf16_f32 v36, v40, v41
	v_cvt_pk_bf16_f32 v37, v38, v39
	global_store_dwordx4 v[46:47], v[34:37], off
	global_load_dwordx4 v[34:37], v[44:45], off offset:512
	s_nop 0
	global_load_dwordx4 v[38:41], v[44:45], off offset:528
	v_mul_f32_e32 v31, v31, v31
	v_mul_f32_e32 v25, v25, v25
	v_mul_f32_e32 v27, v27, v27
	v_fmac_f32_e32 v29, v28, v28
	v_fmac_f32_e32 v31, v30, v30
	v_fmac_f32_e32 v25, v24, v24
	v_fmac_f32_e32 v27, v26, v26
	v_add_f32_e32 v24, v29, v31
	v_add_f32_e32 v25, v25, v27
	v_add_f32_e32 v24, v24, v25
	s_waitcnt vmcnt(1)
	v_pk_fma_f32 v[22:23], v[22:23], v[166:167], v[36:37]
	v_pk_fma_f32 v[20:21], v[20:21], v[168:169], v[34:35]
	s_waitcnt vmcnt(0)
	v_pk_fma_f32 v[18:19], v[18:19], v[162:163], v[40:41]
	v_pk_fma_f32 v[16:17], v[16:17], v[164:165], v[38:39]
	v_mul_f32_e32 v25, v21, v21
	v_mul_f32_e32 v26, v23, v23
	v_mul_f32_e32 v27, v17, v17
	v_mul_f32_e32 v28, v19, v19
	v_fmac_f32_e32 v25, v20, v20
	v_fmac_f32_e32 v26, v22, v22
	v_fmac_f32_e32 v27, v16, v16
	v_fmac_f32_e32 v28, v18, v18
	v_add_f32_e32 v25, v25, v26
	v_add_f32_e32 v26, v27, v28
	v_add_f32_e32 v25, v25, v26
	v_add_f32_e32 v28, v24, v25
	ds_bpermute_b32 v29, v130, v28
	global_store_dwordx4 v[42:43], v[20:23], off offset:512
	global_store_dwordx4 v[42:43], v[16:19], off offset:528
	v_pk_mul_f32 v[26:27], v[72:73], v[16:17]
	v_pk_mul_f32 v[20:21], v[76:77], v[20:21]
	v_pk_mul_f32 v[22:23], v[78:79], v[22:23]
	s_waitcnt lgkmcnt(0)
	v_add_f32_e32 v16, v28, v29
	ds_bpermute_b32 v17, v131, v16
	v_pk_mul_f32 v[24:25], v[74:75], v[18:19]
	v_cvt_pk_bf16_f32 v18, v20, v21
	v_cvt_pk_bf16_f32 v19, v22, v23
	v_cvt_pk_bf16_f32 v20, v26, v27
	s_nop 0
	v_cvt_pk_bf16_f32 v21, v24, v25
	global_store_dwordx4 v[46:47], v[18:21], off offset:256
	s_and_saveexec_b64 s[2:3], vcc
	s_cbranch_execz .LBB0_457
	v_lshl_add_u64 v[18:19], v[32:33], 2, s[10:11]
	s_waitcnt lgkmcnt(0)
	v_add_f32_e32 v16, v16, v17
	v_mov_b32_e32 v236, v16
.LBB0_457:
	s_or_b64 exec, exec, s[2:3]
	v_add_u32_e32 v16, 0xb0, v184
	s_waitcnt lgkmcnt(0)
	v_ashrrev_i32_e32 v17, 31, v16
	v_lshlrev_b64 v[26:27], 13, v[16:17]
	v_lshl_add_u64 v[18:19], s[20:21], 0, v[26:27]
	v_lshl_add_u64 v[28:29], v[18:19], 0, v[182:183]
	global_load_dwordx4 v[18:21], v[28:29], off
	global_load_dwordx4 v[22:25], v[28:29], off offset:16
	v_lshlrev_b64 v[30:31], 12, v[16:17]
	v_lshl_add_u64 v[30:31], s[38:39], 0, v[30:31]
	v_lshl_add_u64 v[26:27], s[90:91], 0, v[26:27]
	v_lshl_add_u64 v[26:27], v[26:27], 0, v[182:183]
	v_lshl_add_u64 v[30:31], v[160:161], 1, v[30:31]
	s_waitcnt vmcnt(1)
	v_pk_fma_f32 v[14:15], v[14:15], v[170:171], v[20:21]
	v_pk_fma_f32 v[12:13], v[12:13], v[176:177], v[18:19]
	s_waitcnt vmcnt(0)
	v_pk_fma_f32 v[10:11], v[10:11], v[178:179], v[24:25]
	v_pk_fma_f32 v[8:9], v[8:9], v[180:181], v[22:23]
	v_pk_mul_f32 v[20:21], v[94:95], v[14:15]
	v_pk_mul_f32 v[18:19], v[92:93], v[12:13]
	global_store_dwordx4 v[26:27], v[12:15], off
	global_store_dwordx4 v[26:27], v[8:11], off offset:16
	v_pk_mul_f32 v[22:23], v[90:91], v[10:11]
	v_pk_mul_f32 v[24:25], v[88:89], v[8:9]
	v_cvt_pk_bf16_f32 v18, v18, v19
	v_cvt_pk_bf16_f32 v19, v20, v21
	v_mul_f32_e32 v13, v13, v13
	v_cvt_pk_bf16_f32 v20, v24, v25
	v_cvt_pk_bf16_f32 v21, v22, v23
	global_store_dwordx4 v[30:31], v[18:21], off
	global_load_dwordx4 v[18:21], v[28:29], off offset:512
	s_nop 0
	global_load_dwordx4 v[22:25], v[28:29], off offset:528
	v_mul_f32_e32 v15, v15, v15
	v_mul_f32_e32 v9, v9, v9
	v_mul_f32_e32 v11, v11, v11
	v_fmac_f32_e32 v13, v12, v12
	v_fmac_f32_e32 v15, v14, v14
	v_fmac_f32_e32 v9, v8, v8
	v_fmac_f32_e32 v11, v10, v10
	v_add_f32_e32 v8, v13, v15
	v_add_f32_e32 v9, v9, v11
	v_add_f32_e32 v8, v8, v9
	s_waitcnt vmcnt(1)
	v_pk_fma_f32 v[6:7], v[6:7], v[166:167], v[20:21]
	v_pk_fma_f32 v[4:5], v[4:5], v[168:169], v[18:19]
	s_waitcnt vmcnt(0)
	v_pk_fma_f32 v[2:3], v[2:3], v[162:163], v[24:25]
	v_pk_fma_f32 v[0:1], v[0:1], v[164:165], v[22:23]
	v_mul_f32_e32 v9, v5, v5
	v_mul_f32_e32 v10, v7, v7
	v_mul_f32_e32 v11, v1, v1
	v_mul_f32_e32 v12, v3, v3
	v_fmac_f32_e32 v9, v4, v4
	v_fmac_f32_e32 v10, v6, v6
	v_fmac_f32_e32 v11, v0, v0
	v_fmac_f32_e32 v12, v2, v2
	v_add_f32_e32 v9, v9, v10
	v_add_f32_e32 v10, v11, v12
	v_add_f32_e32 v9, v9, v10
	v_add_f32_e32 v12, v8, v9
	ds_bpermute_b32 v13, v130, v12
	global_store_dwordx4 v[26:27], v[4:7], off offset:512
	global_store_dwordx4 v[26:27], v[0:3], off offset:528
	v_pk_mul_f32 v[10:11], v[72:73], v[0:1]
	v_pk_mul_f32 v[4:5], v[76:77], v[4:5]
	v_pk_mul_f32 v[6:7], v[78:79], v[6:7]
	s_waitcnt lgkmcnt(0)
	v_add_f32_e32 v0, v12, v13
	ds_bpermute_b32 v1, v131, v0
	v_pk_mul_f32 v[8:9], v[74:75], v[2:3]
	v_cvt_pk_bf16_f32 v2, v4, v5
	v_cvt_pk_bf16_f32 v3, v6, v7
	v_cvt_pk_bf16_f32 v4, v10, v11
	s_nop 0
	v_cvt_pk_bf16_f32 v5, v8, v9
	global_store_dwordx4 v[30:31], v[2:5], off offset:256
	s_and_saveexec_b64 s[2:3], vcc
	s_cbranch_execz .LBB0_459
	v_lshl_add_u64 v[2:3], v[16:17], 2, s[10:11]
	s_waitcnt lgkmcnt(0)
	v_add_f32_e32 v0, v0, v1
	v_mov_b32_e32 v237, v0
.LBB0_459:
	s_or_b64 exec, exec, s[2:3]
	s_and_saveexec_b64 s[2:3], vcc
	global_atomic_add_f32 v[238:239], v230, off
	global_atomic_add_f32 v[238:239], v231, off offset:64
	global_atomic_add_f32 v[238:239], v232, off offset:128
	global_atomic_add_f32 v[238:239], v233, off offset:192
	global_atomic_add_f32 v[238:239], v234, off offset:512
	global_atomic_add_f32 v[238:239], v235, off offset:576
	global_atomic_add_f32 v[238:239], v236, off offset:640
	global_atomic_add_f32 v[238:239], v237, off offset:704
	s_or_b64 exec, exec, s[2:3]
	s_and_b64 vcc, exec, s[0:1]
	s_mov_b64 s[0:1], -1
	s_cbranch_vccnz .LBB0_432
	s_andn2_b64 vcc, exec, s[4:5]
	s_cbranch_vccnz .LBB0_431
	s_barrier
	s_branch .LBB0_431

.LBB0_1150:
	s_or_b64 exec, exec, s[2:3]
	global_store_dwordx2 v[96:97], v[98:99], off
	s_waitcnt vmcnt(1)
	v_mfma_f32_16x16x32_bf16 v[72:75], v[12:15], v[16:19], 0
	s_or_b32 s2, s6, 1
	s_ashr_i32 s3, s2, 31
	s_lshl_b64 s[2:3], s[2:3], 15
	v_mfma_f32_16x16x32_bf16 v[76:79], v[12:15], v[20:23], 0
	v_mfma_f32_16x16x32_bf16 v[80:83], v[12:15], v[24:27], 0
	s_nop 2
	ds_write_b128 v67, v[72:75]
	v_mfma_f32_16x16x32_bf16 v[84:87], v[12:15], v[28:31], 0
	s_nop 1
	ds_write_b128 v67, v[76:79] offset:1280
	ds_write_b128 v67, v[80:83] offset:2560
	s_nop 3
	ds_write_b128 v68, v[84:87]
	v_mfma_f32_16x16x32_bf16 v[88:91], v[12:15], v[32:35], 0
	v_mfma_f32_16x16x32_bf16 v[72:75], v[12:15], v[36:39], 0
	v_mfma_f32_16x16x32_bf16 v[76:79], v[12:15], v[40:43], 0
	s_nop 5
	ds_write_b128 v67, v[88:91] offset:5120
	ds_write_b128 v67, v[72:75] offset:6400
	ds_write_b128 v67, v[76:79] offset:7680
	v_mfma_f32_16x16x32_bf16 v[72:75], v[12:15], v[44:47], 0
	v_mfma_f32_16x16x32_bf16 v[80:83], v[8:11], v[20:23], 0
	v_mfma_f32_16x16x32_bf16 v[84:87], v[8:11], v[24:27], 0
	s_nop 5
	ds_write_b128 v69, v[72:75]
	s_waitcnt lgkmcnt(0)
	ds_read_b128 v[12:15], v70 offset:48
	ds_read_b128 v[72:75], v70 offset:5168
	v_mfma_f32_16x16x32_bf16 v[88:91], v[8:11], v[28:31], 0
	s_waitcnt lgkmcnt(1)
	v_fmamk_f32 v15, v63, 0x80000000, v15
	s_waitcnt lgkmcnt(0)
	v_fma_f32 v50, 0, v63, v75
	v_fmac_f32_e32 v15, 0, v62
	v_fmac_f32_e32 v50, 0, v62
	v_fma_f32 v14, -v63, v50, v14
	v_fmac_f32_e32 v14, v62, v15
	v_fma_f32 v15, v63, v15, v74
	v_fmac_f32_e32 v15, v62, v50
	v_fma_f32 v50, -v63, v15, v13
	v_fma_f32 v71, v63, v14, v73
	v_fmac_f32_e32 v71, v62, v15
	v_fmac_f32_e32 v50, v62, v14
	v_fma_f32 v73, -v63, v71, v12
	s_nop 0
	v_fmac_f32_e32 v73, v62, v50
	ds_read_b128 v[12:15], v70 offset:32
	ds_read_b128 v[74:77], v70 offset:5152
	v_fmac_f32_e32 v72, v63, v50
	v_fmac_f32_e32 v72, v62, v71
	s_waitcnt lgkmcnt(1)
	v_fma_f32 v15, -v63, v72, v15
	s_waitcnt lgkmcnt(0)
	v_fma_f32 v50, v63, v73, v77
	v_fmac_f32_e32 v15, v62, v73
	v_fmac_f32_e32 v50, v62, v72
	v_fma_f32 v14, -v63, v50, v14
	v_fmac_f32_e32 v14, v62, v15
	v_fma_f32 v15, v63, v15, v76
	v_fmac_f32_e32 v15, v62, v50
	v_fma_f32 v50, -v63, v15, v13
	v_fma_f32 v71, v63, v14, v75
	v_fmac_f32_e32 v71, v62, v15
	v_fmac_f32_e32 v50, v62, v14
	v_fma_f32 v72, -v63, v71, v12
	s_nop 0
	v_fmac_f32_e32 v72, v62, v50
	ds_read_b128 v[12:15], v70 offset:16
	ds_read_b128 v[76:79], v70 offset:5136
	v_fmac_f32_e32 v74, v63, v50
	v_fmac_f32_e32 v74, v62, v71
	s_waitcnt lgkmcnt(1)
	v_fma_f32 v15, -v63, v74, v15
	s_waitcnt lgkmcnt(0)
	v_fma_f32 v50, v63, v72, v79
	v_fmac_f32_e32 v15, v62, v72
	v_fmac_f32_e32 v50, v62, v74
	v_fma_f32 v14, -v63, v50, v14
	v_fmac_f32_e32 v14, v62, v15
	v_fma_f32 v15, v63, v15, v78
	v_fmac_f32_e32 v15, v62, v50
	v_fma_f32 v50, -v63, v15, v13
	v_fma_f32 v71, v63, v14, v77
	v_fmac_f32_e32 v71, v62, v15
	v_fmac_f32_e32 v50, v62, v14
	v_fma_f32 v77, -v63, v71, v12
	s_nop 0
	v_fmac_f32_e32 v77, v62, v50
	ds_read_b128 v[12:15], v70
	ds_read_b128 v[72:75], v70 offset:5120
	v_fmac_f32_e32 v76, v63, v50
	v_fmac_f32_e32 v76, v62, v71
	s_waitcnt lgkmcnt(1)
	v_fma_f32 v15, -v63, v76, v15
	s_waitcnt lgkmcnt(0)
	v_fma_f32 v50, v63, v77, v75
	v_fmac_f32_e32 v15, v62, v77
	v_fmac_f32_e32 v50, v62, v76
	v_fma_f32 v14, -v63, v50, v14
	v_fmac_f32_e32 v14, v62, v15
	v_fma_f32 v15, v63, v15, v74
	v_fmac_f32_e32 v15, v62, v50
	v_mfma_f32_16x16x32_bf16 v[76:79], v[8:11], v[16:19], 0
	v_fma_f32 v71, v63, v14, v73
	v_fma_f32 v50, -v63, v15, v13
	v_fmac_f32_e32 v71, v62, v15
	v_fmac_f32_e32 v50, v62, v14
	v_fma_f32 v73, -v63, v71, v12
	v_mfma_f32_16x16x32_bf16 v[12:15], v[8:11], v[32:35], 0
	v_fmac_f32_e32 v73, v62, v50
	s_waitcnt lgkmcnt(0)
	s_nop 0
	ds_write_b128 v67, v[76:79]
	v_mfma_f32_16x16x32_bf16 v[74:77], v[8:11], v[36:39], 0
	ds_write_b128 v67, v[80:83] offset:1280
	ds_write_b128 v67, v[84:87] offset:2560
	ds_write_b128 v68, v[88:91]
	v_fmac_f32_e32 v72, v63, v50
	v_fmac_f32_e32 v72, v62, v71
	v_mfma_f32_16x16x32_bf16 v[78:81], v[8:11], v[40:43], 0
	ds_write_b128 v67, v[12:15] offset:5120
	s_nop 0
	ds_write_b128 v67, v[74:77] offset:6400
	s_nop 4
	ds_write_b128 v67, v[78:81] offset:7680
	v_mfma_f32_16x16x32_bf16 v[12:15], v[8:11], v[44:47], 0
	v_mfma_f32_16x16x32_bf16 v[86:89], v[4:7], v[32:35], 0
	v_mfma_f32_16x16x32_bf16 v[78:81], v[4:7], v[24:27], 0
	s_nop 5
	ds_write_b128 v69, v[12:15]
	s_waitcnt lgkmcnt(0)
	ds_read_b128 v[8:11], v70 offset:48
	ds_read_b128 v[12:15], v70 offset:5168
	v_mfma_f32_16x16x32_bf16 v[82:85], v[4:7], v[28:31], 0
	s_waitcnt lgkmcnt(1)
	v_fma_f32 v11, -v63, v72, v11
	s_waitcnt lgkmcnt(0)
	v_fma_f32 v15, v63, v73, v15
	v_fmac_f32_e32 v11, v62, v73
	v_fmac_f32_e32 v15, v62, v72
	v_fma_f32 v10, -v63, v15, v10
	v_fmac_f32_e32 v10, v62, v11
	v_fma_f32 v11, v63, v11, v14
	v_fmac_f32_e32 v11, v62, v15
	v_fma_f32 v14, -v63, v11, v9
	v_fma_f32 v13, v63, v10, v13
	v_fmac_f32_e32 v13, v62, v11
	v_fmac_f32_e32 v14, v62, v10
	v_fma_f32 v15, -v63, v13, v8
	s_nop 0
	v_fmac_f32_e32 v15, v62, v14
	ds_read_b128 v[8:11], v70 offset:32
	ds_read_b128 v[72:75], v70 offset:5152
	v_fmac_f32_e32 v12, v63, v14
	v_fmac_f32_e32 v12, v62, v13
	s_waitcnt lgkmcnt(1)
	v_fma_f32 v11, -v63, v12, v11
	s_waitcnt lgkmcnt(0)
	v_fma_f32 v13, v63, v15, v75
	v_fmac_f32_e32 v11, v62, v15
	v_fmac_f32_e32 v13, v62, v12
	v_fma_f32 v10, -v63, v13, v10
	v_fmac_f32_e32 v10, v62, v11
	v_fma_f32 v11, v63, v11, v74
	v_fmac_f32_e32 v11, v62, v13
	v_fma_f32 v50, -v63, v11, v9
	v_fma_f32 v71, v63, v10, v73
	v_fmac_f32_e32 v71, v62, v11
	v_fmac_f32_e32 v50, v62, v10
	v_fma_f32 v73, -v63, v71, v8
	s_nop 0
	v_fmac_f32_e32 v73, v62, v50
	ds_read_b128 v[8:11], v70 offset:16
	ds_read_b128 v[12:15], v70 offset:5136
	v_fmac_f32_e32 v72, v63, v50
	v_fmac_f32_e32 v72, v62, v71
	s_waitcnt lgkmcnt(1)
	v_fma_f32 v11, -v63, v72, v11
	s_waitcnt lgkmcnt(0)
	v_fma_f32 v15, v63, v73, v15
	v_fmac_f32_e32 v11, v62, v73
	v_fmac_f32_e32 v15, v62, v72
	v_fma_f32 v10, -v63, v15, v10
	v_fmac_f32_e32 v10, v62, v11
	v_fma_f32 v11, v63, v11, v14
	v_fmac_f32_e32 v11, v62, v15
	v_fma_f32 v14, -v63, v11, v9
	v_fma_f32 v13, v63, v10, v13
	v_fmac_f32_e32 v13, v62, v11
	v_fmac_f32_e32 v14, v62, v10
	v_fma_f32 v15, -v63, v13, v8
	s_nop 0
	v_fmac_f32_e32 v15, v62, v14
	ds_read_b128 v[8:11], v70
	ds_read_b128 v[72:75], v70 offset:5120
	v_fmac_f32_e32 v12, v63, v14
	v_fmac_f32_e32 v12, v62, v13
	s_waitcnt lgkmcnt(1)
	v_fma_f32 v14, -v63, v12, v11
	v_fmac_f32_e32 v14, v62, v15
	s_waitcnt lgkmcnt(0)
	v_fma_f32 v15, v63, v15, v75
	v_fmac_f32_e32 v15, v62, v12
	v_fma_f32 v50, -v63, v15, v10
	v_fmac_f32_e32 v50, v62, v14
	v_fma_f32 v14, v63, v14, v74
	v_fmac_f32_e32 v14, v62, v15
	v_fma_f32 v71, -v63, v14, v9
	v_fmac_f32_e32 v71, v62, v50
	v_fma_f32 v50, v63, v50, v73
	v_mfma_f32_16x16x32_bf16 v[10:13], v[4:7], v[16:19], 0
	v_fmac_f32_e32 v50, v62, v14
	v_fma_f32 v73, -v63, v50, v8
	v_mfma_f32_16x16x32_bf16 v[74:77], v[4:7], v[20:23], 0
	v_fmac_f32_e32 v73, v62, v71
	s_waitcnt lgkmcnt(0)
	s_nop 3
	ds_write_b128 v67, v[10:13]
	v_mfma_f32_16x16x32_bf16 v[8:11], v[4:7], v[36:39], 0
	s_nop 0
	ds_write_b128 v67, v[74:77] offset:1280
	ds_write_b128 v67, v[78:81] offset:2560
	ds_write_b128 v68, v[82:85]
	v_fmac_f32_e32 v72, v63, v71
	v_fmac_f32_e32 v72, v62, v50
	v_mfma_f32_16x16x32_bf16 v[12:15], v[4:7], v[40:43], 0
	ds_write_b128 v67, v[86:89] offset:5120
	ds_write_b128 v67, v[8:11] offset:6400
	s_nop 5
	ds_write_b128 v67, v[12:15] offset:7680
	v_mfma_f32_16x16x32_bf16 v[8:11], v[4:7], v[44:47], 0
	v_mfma_f32_16x16x32_bf16 v[76:79], v[0:3], v[24:27], 0
	v_mfma_f32_16x16x32_bf16 v[80:83], v[0:3], v[28:31], 0
	s_nop 5
	ds_write_b128 v69, v[8:11]
	s_waitcnt lgkmcnt(0)
	ds_read_b128 v[4:7], v70 offset:48
	ds_read_b128 v[8:11], v70 offset:5168
	s_waitcnt lgkmcnt(1)
	v_fma_f32 v7, -v63, v72, v7
	s_waitcnt lgkmcnt(0)
	v_fma_f32 v11, v63, v73, v11
	v_fmac_f32_e32 v7, v62, v73
	v_fmac_f32_e32 v11, v62, v72
	v_fma_f32 v6, -v63, v11, v6
	v_fmac_f32_e32 v6, v62, v7
	v_fma_f32 v7, v63, v7, v10
	v_fmac_f32_e32 v7, v62, v11
	v_fma_f32 v14, -v63, v7, v5
	v_fma_f32 v9, v63, v6, v9
	v_fmac_f32_e32 v9, v62, v7
	v_fmac_f32_e32 v14, v62, v6
	v_fma_f32 v15, -v63, v9, v4
	v_mfma_f32_16x16x32_bf16 v[72:75], v[0:3], v[20:23], 0
	v_fmac_f32_e32 v15, v62, v14
	ds_read_b128 v[4:7], v70 offset:32
	ds_read_b128 v[10:13], v70 offset:5152
	v_fmac_f32_e32 v8, v63, v14
	v_fmac_f32_e32 v8, v62, v9
	s_waitcnt lgkmcnt(1)
	v_fma_f32 v7, -v63, v8, v7
	s_waitcnt lgkmcnt(0)
	v_fma_f32 v9, v63, v15, v13
	v_fmac_f32_e32 v7, v62, v15
	v_fmac_f32_e32 v9, v62, v8
	v_fma_f32 v6, -v63, v9, v6
	v_fmac_f32_e32 v6, v62, v7
	v_fma_f32 v7, v63, v7, v12
	v_fmac_f32_e32 v7, v62, v9
	v_fma_f32 v8, -v63, v7, v5
	v_fma_f32 v9, v63, v6, v11
	v_fmac_f32_e32 v9, v62, v7
	v_fmac_f32_e32 v8, v62, v6
	v_fma_f32 v11, -v63, v9, v4
	s_nop 0
	v_fmac_f32_e32 v11, v62, v8
	ds_read_b128 v[4:7], v70 offset:16
	ds_read_b128 v[12:15], v70 offset:5136
	v_fmac_f32_e32 v10, v63, v8
	v_fmac_f32_e32 v10, v62, v9
	s_waitcnt lgkmcnt(1)
	v_fma_f32 v7, -v63, v10, v7
	s_waitcnt lgkmcnt(0)
	v_fma_f32 v8, v63, v11, v15
	v_fmac_f32_e32 v7, v62, v11
	v_fmac_f32_e32 v8, v62, v10
	v_fma_f32 v6, -v63, v8, v6
	v_fmac_f32_e32 v6, v62, v7
	v_fma_f32 v7, v63, v7, v14
	v_fmac_f32_e32 v7, v62, v8
	v_fma_f32 v14, -v63, v7, v5
	v_fma_f32 v13, v63, v6, v13
	v_fmac_f32_e32 v13, v62, v7
	v_fmac_f32_e32 v14, v62, v6
	v_fma_f32 v15, -v63, v13, v4
	s_nop 0
	v_fmac_f32_e32 v15, v62, v14
	ds_read_b128 v[4:7], v70
	ds_read_b128 v[8:11], v70 offset:5120
	v_fmac_f32_e32 v12, v63, v14
	v_fmac_f32_e32 v12, v62, v13
	s_waitcnt lgkmcnt(1)
	v_fma_f32 v7, -v63, v12, v7
	s_waitcnt lgkmcnt(0)
	v_fma_f32 v11, v63, v15, v11
	v_fmac_f32_e32 v7, v62, v15
	v_fmac_f32_e32 v11, v62, v12
	v_fma_f32 v6, -v63, v11, v6
	v_fmac_f32_e32 v6, v62, v7
	v_fma_f32 v7, v63, v7, v10
	v_fmac_f32_e32 v7, v62, v11
	v_mfma_f32_16x16x32_bf16 v[12:15], v[0:3], v[16:19], 0
	v_fma_f32 v9, v63, v6, v9
	v_fma_f32 v50, -v63, v7, v5
	v_fmac_f32_e32 v9, v62, v7
	v_fmac_f32_e32 v50, v62, v6
	v_fma_f32 v71, -v63, v9, v4
	v_mfma_f32_16x16x32_bf16 v[4:7], v[0:3], v[32:35], 0
	v_fmac_f32_e32 v71, v62, v50
	s_waitcnt lgkmcnt(0)
	s_nop 0
	ds_write_b128 v67, v[12:15]
	v_mfma_f32_16x16x32_bf16 v[10:13], v[0:3], v[36:39], 0
	ds_write_b128 v67, v[72:75] offset:1280
	ds_write_b128 v67, v[76:79] offset:2560
	ds_write_b128 v68, v[80:83]
	v_fmac_f32_e32 v8, v63, v50
	v_fmac_f32_e32 v8, v62, v9
	v_mfma_f32_16x16x32_bf16 v[72:75], v[0:3], v[40:43], 0
	ds_write_b128 v67, v[4:7] offset:5120
	s_nop 0
	ds_write_b128 v67, v[10:13] offset:6400
	s_nop 4
	ds_write_b128 v67, v[72:75] offset:7680
	v_mfma_f32_16x16x32_bf16 v[4:7], v[0:3], v[44:47], 0
	s_nop 7
	ds_write_b128 v69, v[4:7]
	s_waitcnt lgkmcnt(0)
	ds_read_b128 v[0:3], v70 offset:48
	ds_read_b128 v[4:7], v70 offset:5168
	s_waitcnt lgkmcnt(1)
	v_fma_f32 v3, -v63, v8, v3
	s_waitcnt lgkmcnt(0)
	v_fma_f32 v7, v63, v71, v7
	v_fmac_f32_e32 v3, v62, v71
	v_fmac_f32_e32 v7, v62, v8
	v_fma_f32 v2, -v63, v7, v2
	v_fmac_f32_e32 v2, v62, v3
	v_fma_f32 v3, v63, v3, v6
	v_fmac_f32_e32 v3, v62, v7
	v_fma_f32 v10, -v63, v3, v1
	v_fma_f32 v5, v63, v2, v5
	v_fmac_f32_e32 v5, v62, v3
	v_fmac_f32_e32 v10, v62, v2
	v_fma_f32 v11, -v63, v5, v0
	s_nop 0
	v_fmac_f32_e32 v11, v62, v10
	ds_read_b128 v[0:3], v70 offset:32
	ds_read_b128 v[6:9], v70 offset:5152
	v_fmac_f32_e32 v4, v63, v10
	v_fmac_f32_e32 v4, v62, v5
	s_waitcnt lgkmcnt(1)
	v_fma_f32 v3, -v63, v4, v3
	s_waitcnt lgkmcnt(0)
	v_fma_f32 v5, v63, v11, v9
	v_fmac_f32_e32 v3, v62, v11
	v_fmac_f32_e32 v5, v62, v4
	v_fma_f32 v2, -v63, v5, v2
	v_fmac_f32_e32 v2, v62, v3
	v_fma_f32 v3, v63, v3, v8
	v_fmac_f32_e32 v3, v62, v5
	v_fma_f32 v4, -v63, v3, v1
	v_fma_f32 v5, v63, v2, v7
	v_fmac_f32_e32 v5, v62, v3
	v_fmac_f32_e32 v4, v62, v2
	v_fma_f32 v7, -v63, v5, v0
	s_nop 0
	v_fmac_f32_e32 v7, v62, v4
	ds_read_b128 v[0:3], v70 offset:16
	ds_read_b128 v[8:11], v70 offset:5136
	v_fmac_f32_e32 v6, v63, v4
	v_fmac_f32_e32 v6, v62, v5
	s_waitcnt lgkmcnt(1)
	v_fma_f32 v3, -v63, v6, v3
	s_waitcnt lgkmcnt(0)
	v_fma_f32 v4, v63, v7, v11
	v_fmac_f32_e32 v3, v62, v7
	v_fmac_f32_e32 v4, v62, v6
	v_fma_f32 v2, -v63, v4, v2
	v_fmac_f32_e32 v2, v62, v3
	v_fma_f32 v3, v63, v3, v10
	v_fmac_f32_e32 v3, v62, v4
	v_fma_f32 v10, -v63, v3, v1
	v_fma_f32 v9, v63, v2, v9
	v_fmac_f32_e32 v9, v62, v3
	v_fmac_f32_e32 v10, v62, v2
	v_fma_f32 v11, -v63, v9, v0
	s_nop 0
	v_fmac_f32_e32 v11, v62, v10
	ds_read_b128 v[0:3], v70
	ds_read_b128 v[4:7], v70 offset:5120
	v_fmac_f32_e32 v8, v63, v10
	v_fmac_f32_e32 v8, v62, v9
	s_waitcnt lgkmcnt(1)
	v_fma_f32 v3, -v63, v8, v3
	s_waitcnt lgkmcnt(0)
	v_fma_f32 v7, v63, v11, v7
	v_fmac_f32_e32 v3, v62, v11
	v_fmac_f32_e32 v7, v62, v8
	v_fma_f32 v2, -v63, v7, v2
	v_fmac_f32_e32 v2, v62, v3
	v_fma_f32 v3, v63, v3, v6
	v_fmac_f32_e32 v3, v62, v7
	v_fma_f32 v1, -v63, v3, v1
	v_fmac_f32_e32 v1, v62, v2
	v_fma_f32 v2, v63, v2, v5
	v_fmac_f32_e32 v2, v62, v3
	v_fma_f32 v0, -v63, v2, v0
	s_nop 0
	v_fmac_f32_e32 v0, v62, v1
	v_fmac_f32_e32 v4, v63, v1
	s_waitcnt lgkmcnt(0)
	v_fmac_f32_e32 v4, v62, v2
	v_lshl_add_u64 v[2:3], v[60:61], 0, s[2:3]
	v_readlane_b32 s2, v243, 40
	s_add_i32 s4, s4, s2
	v_mov_b32_e32 v1, v4
	s_cmpk_gt_i32 s4, 0x5fff
	v_readlane_b32 s3, v243, 41
	global_store_dwordx2 v[2:3], v[0:1], off
	s_cbranch_scc1 .LBB0_1191

.LBB0_1175:
	s_or_b64 exec, exec, s[2:3]
	s_waitcnt vmcnt(0)
	v_mfma_f32_16x16x32_bf16 v[72:75], v[0:3], v[20:23], 0
	s_ashr_i32 s6, s4, 5
	s_and_b32 s2, s6, -2
	s_lshl_b32 s0, s0, 3
	v_mfma_f32_16x16x32_bf16 v[76:79], v[0:3], v[16:19], 0
	s_ashr_i32 s3, s2, 31
	s_nop 2
	ds_write_b128 v67, v[72:75]
	s_lshl_b64 s[2:3], s[2:3], 15
	v_mfma_f32_16x16x32_bf16 v[80:83], v[0:3], v[24:27], 0
	v_mfma_f32_16x16x32_bf16 v[84:87], v[0:3], v[28:31], 0
	ds_write_b128 v67, v[76:79] offset:1280
	s_nop 5
	ds_write_b128 v67, v[80:83] offset:2560
	ds_write_b128 v68, v[84:87]
	v_mfma_f32_16x16x32_bf16 v[88:91], v[0:3], v[32:35], 0
	v_mfma_f32_16x16x32_bf16 v[72:75], v[0:3], v[36:39], 0
	v_mfma_f32_16x16x32_bf16 v[76:79], v[0:3], v[40:43], 0
	s_nop 5
	ds_write_b128 v67, v[88:91] offset:5120
	ds_write_b128 v67, v[72:75] offset:6400
	ds_write_b128 v67, v[76:79] offset:7680
	v_mfma_f32_16x16x32_bf16 v[72:75], v[0:3], v[44:47], 0
	v_mfma_f32_16x16x32_bf16 v[84:87], v[4:7], v[16:19], 0
	v_mfma_f32_16x16x32_bf16 v[88:91], v[4:7], v[24:27], 0
	s_nop 5
	ds_write_b128 v69, v[72:75]
	s_waitcnt lgkmcnt(0)
	ds_read_b128 v[72:75], v70
	ds_read_b128 v[76:79], v70 offset:5120
	v_mfma_f32_16x16x32_bf16 v[92:95], v[4:7], v[28:31], 0
	s_waitcnt lgkmcnt(1)
	v_fmamk_f32 v50, v63, 0x80000000, v72
	s_waitcnt lgkmcnt(0)
	v_fma_f32 v60, 0, v63, v76
	v_fmac_f32_e32 v50, 0, v62
	v_fmac_f32_e32 v60, 0, v62
	v_fma_f32 v61, -v63, v60, v73
	v_fmac_f32_e32 v61, v62, v50
	v_fma_f32 v50, v63, v50, v77
	v_fmac_f32_e32 v50, v62, v60
	v_fma_f32 v60, -v63, v50, v74
	v_fmac_f32_e32 v60, v62, v61
	v_fma_f32 v61, v63, v61, v78
	v_fmac_f32_e32 v61, v62, v50
	v_fma_f32 v50, -v63, v61, v75
	s_nop 0
	v_fmac_f32_e32 v50, v62, v60
	ds_read_b128 v[72:75], v70 offset:16
	ds_read_b128 v[80:83], v70 offset:5136
	v_fmac_f32_e32 v79, v63, v60
	v_fmac_f32_e32 v79, v62, v61
	s_waitcnt lgkmcnt(1)
	v_fma_f32 v60, -v63, v79, v72
	v_fmac_f32_e32 v60, v62, v50
	s_waitcnt lgkmcnt(0)
	v_fma_f32 v50, v63, v50, v80
	v_fmac_f32_e32 v50, v62, v79
	v_fma_f32 v61, -v63, v50, v73
	v_fmac_f32_e32 v61, v62, v60
	v_fma_f32 v60, v63, v60, v81
	v_fmac_f32_e32 v60, v62, v50
	v_fma_f32 v50, -v63, v60, v74
	v_fmac_f32_e32 v50, v62, v61
	v_fma_f32 v61, v63, v61, v82
	v_fmac_f32_e32 v61, v62, v60
	v_fma_f32 v60, -v63, v61, v75
	s_nop 0
	v_fmac_f32_e32 v60, v62, v50
	ds_read_b128 v[72:75], v70 offset:32
	ds_read_b128 v[76:79], v70 offset:5152
	v_fmac_f32_e32 v83, v63, v50
	v_fmac_f32_e32 v83, v62, v61
	s_waitcnt lgkmcnt(1)
	v_fma_f32 v50, -v63, v83, v72
	v_fmac_f32_e32 v50, v62, v60
	s_waitcnt lgkmcnt(0)
	v_fma_f32 v60, v63, v60, v76
	v_fmac_f32_e32 v60, v62, v83
	v_fma_f32 v61, -v63, v60, v73
	v_fmac_f32_e32 v61, v62, v50
	v_fma_f32 v50, v63, v50, v77
	v_fmac_f32_e32 v50, v62, v60
	v_fma_f32 v60, -v63, v50, v74
	v_fmac_f32_e32 v60, v62, v61
	v_fma_f32 v61, v63, v61, v78
	v_fmac_f32_e32 v61, v62, v50
	v_fma_f32 v50, -v63, v61, v75
	s_nop 0
	v_fmac_f32_e32 v50, v62, v60
	ds_read_b128 v[72:75], v70 offset:48
	ds_read_b128 v[80:83], v70 offset:5168
	v_fmac_f32_e32 v79, v63, v60
	v_fmac_f32_e32 v79, v62, v61
	s_waitcnt lgkmcnt(1)
	v_fma_f32 v60, -v63, v79, v72
	v_fmac_f32_e32 v60, v62, v50
	s_waitcnt lgkmcnt(0)
	v_fma_f32 v50, v63, v50, v80
	v_fmac_f32_e32 v50, v62, v79
	v_fma_f32 v61, -v63, v50, v73
	v_fmac_f32_e32 v61, v62, v60
	v_fma_f32 v60, v63, v60, v81
	v_fmac_f32_e32 v60, v62, v50
	v_fma_f32 v50, -v63, v60, v74
	v_fmac_f32_e32 v50, v62, v61
	v_fma_f32 v61, v63, v61, v82
	v_mfma_f32_16x16x32_bf16 v[76:79], v[4:7], v[20:23], 0
	v_fmac_f32_e32 v61, v62, v60
	v_fma_f32 v60, -v63, v61, v75
	v_mfma_f32_16x16x32_bf16 v[72:75], v[4:7], v[32:35], 0
	v_fmac_f32_e32 v60, v62, v50
	s_waitcnt lgkmcnt(0)
	s_nop 3
	ds_write_b128 v67, v[76:79]
	v_mfma_f32_16x16x32_bf16 v[76:79], v[4:7], v[36:39], 0
	ds_write_b128 v67, v[84:87] offset:1280
	ds_write_b128 v67, v[88:91] offset:2560
	ds_write_b128 v68, v[92:95]
	v_fmac_f32_e32 v83, v63, v50
	v_fmac_f32_e32 v83, v62, v61
	v_mfma_f32_16x16x32_bf16 v[84:87], v[4:7], v[40:43], 0
	ds_write_b128 v67, v[72:75] offset:5120
	s_nop 0
	ds_write_b128 v67, v[76:79] offset:6400
	s_nop 4
	ds_write_b128 v67, v[84:87] offset:7680
	v_mfma_f32_16x16x32_bf16 v[72:75], v[4:7], v[44:47], 0
	v_mfma_f32_16x16x32_bf16 v[84:87], v[8:11], v[16:19], 0
	v_mfma_f32_16x16x32_bf16 v[88:91], v[8:11], v[24:27], 0
	s_nop 5
	ds_write_b128 v69, v[72:75]
	s_waitcnt lgkmcnt(0)
	ds_read_b128 v[72:75], v70
	ds_read_b128 v[76:79], v70 offset:5120
	v_mfma_f32_16x16x32_bf16 v[92:95], v[8:11], v[28:31], 0
	s_waitcnt lgkmcnt(1)
	v_fma_f32 v50, -v63, v83, v72
	v_fmac_f32_e32 v50, v62, v60
	s_waitcnt lgkmcnt(0)
	v_fma_f32 v60, v63, v60, v76
	v_fmac_f32_e32 v60, v62, v83
	v_fma_f32 v61, -v63, v60, v73
	v_fmac_f32_e32 v61, v62, v50
	v_fma_f32 v50, v63, v50, v77
	v_fmac_f32_e32 v50, v62, v60
	v_fma_f32 v60, -v63, v50, v74
	v_fmac_f32_e32 v60, v62, v61
	v_fma_f32 v61, v63, v61, v78
	v_fmac_f32_e32 v61, v62, v50
	v_fma_f32 v50, -v63, v61, v75
	s_nop 0
	v_fmac_f32_e32 v50, v62, v60
	ds_read_b128 v[72:75], v70 offset:16
	ds_read_b128 v[80:83], v70 offset:5136
	v_fmac_f32_e32 v79, v63, v60
	v_fmac_f32_e32 v79, v62, v61
	s_waitcnt lgkmcnt(1)
	v_fma_f32 v60, -v63, v79, v72
	v_fmac_f32_e32 v60, v62, v50
	s_waitcnt lgkmcnt(0)
	v_fma_f32 v50, v63, v50, v80
	v_fmac_f32_e32 v50, v62, v79
	v_fma_f32 v61, -v63, v50, v73
	v_fmac_f32_e32 v61, v62, v60
	v_fma_f32 v60, v63, v60, v81
	v_fmac_f32_e32 v60, v62, v50
	v_fma_f32 v50, -v63, v60, v74
	v_fmac_f32_e32 v50, v62, v61
	v_fma_f32 v61, v63, v61, v82
	v_fmac_f32_e32 v61, v62, v60
	v_fma_f32 v60, -v63, v61, v75
	s_nop 0
	v_fmac_f32_e32 v60, v62, v50
	ds_read_b128 v[72:75], v70 offset:32
	ds_read_b128 v[76:79], v70 offset:5152
	v_fmac_f32_e32 v83, v63, v50
	v_fmac_f32_e32 v83, v62, v61
	s_waitcnt lgkmcnt(1)
	v_fma_f32 v50, -v63, v83, v72
	v_fmac_f32_e32 v50, v62, v60
	s_waitcnt lgkmcnt(0)
	v_fma_f32 v60, v63, v60, v76
	v_fmac_f32_e32 v60, v62, v83
	v_fma_f32 v61, -v63, v60, v73
	v_fmac_f32_e32 v61, v62, v50
	v_fma_f32 v50, v63, v50, v77
	v_fmac_f32_e32 v50, v62, v60
	v_fma_f32 v60, -v63, v50, v74
	v_fmac_f32_e32 v60, v62, v61
	v_fma_f32 v61, v63, v61, v78
	v_fmac_f32_e32 v61, v62, v50
	v_fma_f32 v50, -v63, v61, v75
	s_nop 0
	v_fmac_f32_e32 v50, v62, v60
	ds_read_b128 v[72:75], v70 offset:48
	ds_read_b128 v[80:83], v70 offset:5168
	v_fmac_f32_e32 v79, v63, v60
	v_fmac_f32_e32 v79, v62, v61
	s_waitcnt lgkmcnt(1)
	v_fma_f32 v60, -v63, v79, v72
	v_fmac_f32_e32 v60, v62, v50
	s_waitcnt lgkmcnt(0)
	v_fma_f32 v50, v63, v50, v80
	v_fmac_f32_e32 v50, v62, v79
	v_fma_f32 v61, -v63, v50, v73
	v_fmac_f32_e32 v61, v62, v60
	v_fma_f32 v60, v63, v60, v81
	v_fmac_f32_e32 v60, v62, v50
	v_fma_f32 v50, -v63, v60, v74
	v_fmac_f32_e32 v50, v62, v61
	v_fma_f32 v61, v63, v61, v82
	v_mfma_f32_16x16x32_bf16 v[76:79], v[8:11], v[20:23], 0
	v_fmac_f32_e32 v61, v62, v60
	v_fma_f32 v60, -v63, v61, v75
	v_mfma_f32_16x16x32_bf16 v[72:75], v[8:11], v[32:35], 0
	v_fmac_f32_e32 v60, v62, v50
	s_waitcnt lgkmcnt(0)
	s_nop 3
	ds_write_b128 v67, v[76:79]
	v_mfma_f32_16x16x32_bf16 v[76:79], v[8:11], v[36:39], 0
	ds_write_b128 v67, v[84:87] offset:1280
	ds_write_b128 v67, v[88:91] offset:2560
	ds_write_b128 v68, v[92:95]
	v_fmac_f32_e32 v83, v63, v50
	v_fmac_f32_e32 v83, v62, v61
	v_mfma_f32_16x16x32_bf16 v[84:87], v[8:11], v[40:43], 0
	ds_write_b128 v67, v[72:75] offset:5120
	s_nop 0
	ds_write_b128 v67, v[76:79] offset:6400
	s_nop 4
	ds_write_b128 v67, v[84:87] offset:7680
	v_mfma_f32_16x16x32_bf16 v[72:75], v[8:11], v[44:47], 0
	v_mfma_f32_16x16x32_bf16 v[84:87], v[12:15], v[16:19], 0
	v_mfma_f32_16x16x32_bf16 v[88:91], v[12:15], v[24:27], 0
	s_nop 5
	ds_write_b128 v69, v[72:75]
	s_waitcnt lgkmcnt(0)
	ds_read_b128 v[72:75], v70
	ds_read_b128 v[76:79], v70 offset:5120
	v_mfma_f32_16x16x32_bf16 v[92:95], v[12:15], v[28:31], 0
	s_waitcnt lgkmcnt(1)
	v_fma_f32 v50, -v63, v83, v72
	v_fmac_f32_e32 v50, v62, v60
	s_waitcnt lgkmcnt(0)
	v_fma_f32 v60, v63, v60, v76
	v_fmac_f32_e32 v60, v62, v83
	v_fma_f32 v61, -v63, v60, v73
	v_fmac_f32_e32 v61, v62, v50
	v_fma_f32 v50, v63, v50, v77
	v_fmac_f32_e32 v50, v62, v60
	v_fma_f32 v60, -v63, v50, v74
	v_fmac_f32_e32 v60, v62, v61
	v_fma_f32 v61, v63, v61, v78
	v_fmac_f32_e32 v61, v62, v50
	v_fma_f32 v50, -v63, v61, v75
	s_nop 0
	v_fmac_f32_e32 v50, v62, v60
	ds_read_b128 v[72:75], v70 offset:16
	ds_read_b128 v[80:83], v70 offset:5136
	v_fmac_f32_e32 v79, v63, v60
	v_fmac_f32_e32 v79, v62, v61
	s_waitcnt lgkmcnt(1)
	v_fma_f32 v60, -v63, v79, v72
	v_fmac_f32_e32 v60, v62, v50
	s_waitcnt lgkmcnt(0)
	v_fma_f32 v50, v63, v50, v80
	v_fmac_f32_e32 v50, v62, v79
	v_fma_f32 v61, -v63, v50, v73
	v_fmac_f32_e32 v61, v62, v60
	v_fma_f32 v60, v63, v60, v81
	v_fmac_f32_e32 v60, v62, v50
	v_fma_f32 v50, -v63, v60, v74
	v_fmac_f32_e32 v50, v62, v61
	v_fma_f32 v61, v63, v61, v82
	v_fmac_f32_e32 v61, v62, v60
	v_fma_f32 v60, -v63, v61, v75
	s_nop 0
	v_fmac_f32_e32 v60, v62, v50
	ds_read_b128 v[72:75], v70 offset:32
	ds_read_b128 v[76:79], v70 offset:5152
	v_fmac_f32_e32 v83, v63, v50
	v_fmac_f32_e32 v83, v62, v61
	s_waitcnt lgkmcnt(1)
	v_fma_f32 v50, -v63, v83, v72
	v_fmac_f32_e32 v50, v62, v60
	s_waitcnt lgkmcnt(0)
	v_fma_f32 v60, v63, v60, v76
	v_fmac_f32_e32 v60, v62, v83
	v_fma_f32 v61, -v63, v60, v73
	v_fmac_f32_e32 v61, v62, v50
	v_fma_f32 v50, v63, v50, v77
	v_fmac_f32_e32 v50, v62, v60
	v_fma_f32 v60, -v63, v50, v74
	v_fmac_f32_e32 v60, v62, v61
	v_fma_f32 v61, v63, v61, v78
	v_fmac_f32_e32 v61, v62, v50
	v_fma_f32 v50, -v63, v61, v75
	s_nop 0
	v_fmac_f32_e32 v50, v62, v60
	ds_read_b128 v[72:75], v70 offset:48
	ds_read_b128 v[80:83], v70 offset:5168
	v_fmac_f32_e32 v79, v63, v60
	v_fmac_f32_e32 v79, v62, v61
	s_waitcnt lgkmcnt(1)
	v_fma_f32 v60, -v63, v79, v72
	v_fmac_f32_e32 v60, v62, v50
	s_waitcnt lgkmcnt(0)
	v_fma_f32 v50, v63, v50, v80
	v_fmac_f32_e32 v50, v62, v79
	v_fma_f32 v61, -v63, v50, v73
	v_fmac_f32_e32 v61, v62, v60
	v_fma_f32 v60, v63, v60, v81
	v_fmac_f32_e32 v60, v62, v50
	v_fma_f32 v50, -v63, v60, v74
	v_fmac_f32_e32 v50, v62, v61
	v_fma_f32 v61, v63, v61, v82
	v_mfma_f32_16x16x32_bf16 v[76:79], v[12:15], v[20:23], 0
	v_fmac_f32_e32 v61, v62, v60
	v_fma_f32 v60, -v63, v61, v75
	v_mfma_f32_16x16x32_bf16 v[72:75], v[12:15], v[32:35], 0
	v_fmac_f32_e32 v60, v62, v50
	s_waitcnt lgkmcnt(0)
	s_nop 3
	ds_write_b128 v67, v[76:79]
	v_mfma_f32_16x16x32_bf16 v[76:79], v[12:15], v[36:39], 0
	ds_write_b128 v67, v[84:87] offset:1280
	ds_write_b128 v67, v[88:91] offset:2560
	ds_write_b128 v68, v[92:95]
	v_fmac_f32_e32 v83, v63, v50
	v_fmac_f32_e32 v83, v62, v61
	v_mfma_f32_16x16x32_bf16 v[84:87], v[12:15], v[40:43], 0
	ds_write_b128 v67, v[72:75] offset:5120
	s_nop 0
	ds_write_b128 v67, v[76:79] offset:6400
	s_nop 4
	ds_write_b128 v67, v[84:87] offset:7680
	v_mfma_f32_16x16x32_bf16 v[72:75], v[12:15], v[44:47], 0
	s_nop 7
	ds_write_b128 v69, v[72:75]
	s_waitcnt lgkmcnt(0)
	ds_read_b128 v[16:19], v70
	ds_read_b128 v[20:23], v70 offset:5120
	s_waitcnt lgkmcnt(1)
	v_fma_f32 v16, -v63, v83, v16
	s_waitcnt lgkmcnt(0)
	v_fma_f32 v20, v63, v60, v20
	v_fmac_f32_e32 v16, v62, v60
	v_fmac_f32_e32 v20, v62, v83
	v_fma_f32 v17, -v63, v20, v17
	v_fmac_f32_e32 v17, v62, v16
	v_fma_f32 v16, v63, v16, v21
	v_fmac_f32_e32 v16, v62, v20
	v_fma_f32 v20, -v63, v16, v18
	v_fma_f32 v21, v63, v17, v22
	v_fmac_f32_e32 v21, v62, v16
	v_fmac_f32_e32 v20, v62, v17
	v_fma_f32 v22, -v63, v21, v19
	v_lshl_add_u64 v[60:61], v[58:59], 0, s[0:1]
	v_fmac_f32_e32 v22, v62, v20
	ds_read_b128 v[16:19], v70 offset:16
	ds_read_b128 v[24:27], v70 offset:5136
	v_fmac_f32_e32 v23, v63, v20
	v_fmac_f32_e32 v23, v62, v21
	s_or_b32 s0, s5, 64
	s_waitcnt lgkmcnt(1)
	v_fma_f32 v16, -v63, v23, v16
	s_waitcnt lgkmcnt(0)
	v_fma_f32 v20, v63, v22, v24
	v_fmac_f32_e32 v16, v62, v22
	v_fmac_f32_e32 v20, v62, v23
	v_fma_f32 v17, -v63, v20, v17
	v_fmac_f32_e32 v17, v62, v16
	v_fma_f32 v16, v63, v16, v25
	v_fmac_f32_e32 v16, v62, v20
	v_fma_f32 v24, -v63, v16, v18
	v_fma_f32 v25, v63, v17, v26
	v_fmac_f32_e32 v25, v62, v16
	v_fmac_f32_e32 v24, v62, v17
	v_fma_f32 v26, -v63, v25, v19
	v_lshl_or_b32 v50, s0, 12, v49
	v_fmac_f32_e32 v26, v62, v24
	ds_read_b128 v[16:19], v70 offset:32
	ds_read_b128 v[20:23], v70 offset:5152
	v_fmac_f32_e32 v27, v63, v24
	v_fmac_f32_e32 v27, v62, v25
	s_waitcnt lgkmcnt(1)
	v_fma_f32 v16, -v63, v27, v16
	s_waitcnt lgkmcnt(0)
	v_fma_f32 v20, v63, v26, v20
	v_fmac_f32_e32 v16, v62, v26
	v_fmac_f32_e32 v20, v62, v27
	v_fma_f32 v17, -v63, v20, v17
	v_fmac_f32_e32 v17, v62, v16
	v_fma_f32 v16, v63, v16, v21
	v_fmac_f32_e32 v16, v62, v20
	v_fma_f32 v20, -v63, v16, v18
	v_fma_f32 v21, v63, v17, v22
	v_fmac_f32_e32 v21, v62, v16
	v_fmac_f32_e32 v20, v62, v17
	v_fma_f32 v22, -v63, v21, v19
	s_nop 0
	v_fmac_f32_e32 v22, v62, v20
	ds_read_b128 v[16:19], v70 offset:48
	ds_read_b128 v[24:27], v70 offset:5168
	v_fmac_f32_e32 v23, v63, v20
	v_fmac_f32_e32 v23, v62, v21
	s_waitcnt lgkmcnt(1)
	v_fma_f32 v16, -v63, v23, v16
	s_waitcnt lgkmcnt(0)
	v_fma_f32 v20, v63, v22, v24
	v_fmac_f32_e32 v16, v62, v22
	v_fmac_f32_e32 v20, v62, v23
	v_fma_f32 v17, -v63, v20, v17
	v_fmac_f32_e32 v17, v62, v16
	v_fma_f32 v16, v63, v16, v25
	v_fmac_f32_e32 v16, v62, v20
	v_fma_f32 v18, -v63, v16, v18
	v_fmac_f32_e32 v18, v62, v17
	v_fma_f32 v17, v63, v17, v26
	v_fmac_f32_e32 v17, v62, v16
	v_fma_f32 v26, -v63, v17, v19
	v_mov_b32_e32 v20, 0
	v_fmac_f32_e32 v26, v62, v18
	v_fmac_f32_e32 v27, v63, v18
	v_fmac_f32_e32 v27, v62, v17
	s_waitcnt lgkmcnt(0)
	v_lshl_add_u64 v[16:17], v[60:61], 0, s[2:3]
	v_mov_b32_e32 v96, v16
	v_mov_b32_e32 v97, v17
	v_mov_b32_e32 v98, v26
	v_mov_b32_e32 v99, v27
	v_lshl_or_b32 v16, s0, 9, v56
	global_load_dwordx2 v[62:63], v16, s[92:93]
	v_mov_b32_e32 v16, 0
	v_mov_b32_e32 v17, 0
	v_mov_b32_e32 v18, 0
	v_mov_b32_e32 v19, 0
	s_and_saveexec_b64 s[2:3], vcc
	s_cbranch_execz .LBB0_1177
	v_lshl_add_u64 v[16:17], v[54:55], 0, v[50:51]
	global_load_dwordx4 v[16:19], v[16:17], off

.LBB0_2032:
	s_lshl_b32 s3, s24, 8
	s_add_i32 s17, s3, 0xffffe000
	s_ashr_i32 s17, s17, 12
	s_add_i32 s17, s17, 1
	s_cmp_gt_i32 s24, 31
	s_cselect_b32 s17, s17, 0
	s_mul_i32 s24, s17, 0x12000
	v_readlane_b32 s26, v243, 42
	s_mul_hi_i32 s19, s17, 0x12000
	v_readlane_b32 s27, v243, 43
	s_add_u32 s26, s26, s24
	s_addc_u32 s27, s27, s19
	s_lshl_b32 s2, s2, 8
	v_mov_b32_e32 v78, v173
	v_mov_b32_e32 v189, v175
	s_or_b32 s2, s2, s46
	s_add_i32 s19, s3, s45
	v_lshl_add_u32 v180, v189, 3, s2
	v_ashrrev_i32_e32 v181, 31, v180
	v_add_u32_e32 v182, s19, v78
	v_lshlrev_b64 v[76:77], 2, v[180:181]
	s_lshl_b32 s2, s17, 11
	v_ashrrev_i32_e32 v183, 31, v182
	v_lshl_add_u64 v[72:73], s[26:27], 0, v[76:77]
	s_ashr_i32 s3, s2, 31
	v_lshlrev_b64 v[78:79], 13, v[182:183]
	v_lshl_add_u64 v[84:85], v[72:73], 0, s[14:15]
	v_add_co_u32_e32 v72, vcc, s49, v72
	v_lshl_add_u64 v[78:79], s[90:91], 0, v[78:79]
	s_lshl_b64 s[2:3], s[2:3], 2
	v_addc_co_u32_e32 v73, vcc, 0, v73, vcc
	v_lshl_add_u64 v[202:203], v[78:79], 0, v[76:77]
	s_add_u32 s2, s53, s2
	global_load_dwordx4 v[72:75], v[72:73], off
	s_nop 0
	global_load_dwordx4 v[190:193], v[202:203], off offset:16
	global_load_dwordx4 v[194:197], v[202:203], off
	s_addc_u32 s3, s54, s3
	global_load_dwordx4 v[100:103], v[84:85], off offset:16
	v_lshl_add_u64 v[86:87], s[2:3], 0, v[76:77]
	global_load_dwordx4 v[96:99], v[86:87], off
	global_load_dwordx4 v[92:95], v[86:87], off offset:16
	v_lshlrev_b64 v[76:77], 12, v[182:183]
	v_lshl_add_u64 v[76:77], s[38:39], 0, v[76:77]
	v_lshl_add_u64 v[204:205], v[180:181], 1, v[76:77]
	global_load_dwordx4 v[76:79], v[86:87], off offset:512
	global_load_dwordx4 v[104:107], v[84:85], off offset:528
	global_load_dwordx4 v[108:111], v[84:85], off offset:512
	s_nop 0
	global_load_dwordx4 v[84:87], v[86:87], off offset:528
	v_cmp_eq_u32_e32 vcc, 0, v189
	s_waitcnt vmcnt(0)
	v_pk_fma_f32 v[158:159], v[158:159], v[74:75], v[196:197]
	v_pk_fma_f32 v[156:157], v[156:157], v[72:73], v[194:195]
	v_pk_fma_f32 v[192:193], v[154:155], v[102:103], v[192:193]
	v_pk_fma_f32 v[190:191], v[152:153], v[100:101], v[190:191]
	v_pk_mul_f32 v[154:155], v[98:99], v[158:159]
	v_pk_mul_f32 v[152:153], v[96:97], v[156:157]
	global_store_dwordx4 v[202:203], v[156:159], off
	global_store_dwordx4 v[202:203], v[190:193], off offset:16
	v_pk_mul_f32 v[194:195], v[94:95], v[192:193]
	v_pk_mul_f32 v[196:197], v[92:93], v[190:191]
	v_cvt_pk_bf16_f32 v152, v152, v153
	v_cvt_pk_bf16_f32 v153, v154, v155
	s_nop 0
	v_cvt_pk_bf16_f32 v154, v196, v197
	v_cvt_pk_bf16_f32 v155, v194, v195
	global_store_dwordx4 v[204:205], v[152:155], off
	global_load_dwordx4 v[194:197], v[202:203], off offset:512
	global_load_dwordx4 v[198:201], v[202:203], off offset:528
	v_and_b32_e32 v153, 64, v188
	v_xor_b32_e32 v152, 16, v188
	v_add_u32_e32 v153, 64, v153
	v_xor_b32_e32 v154, 32, v188
	v_cmp_lt_i32_e64 s[2:3], v152, v153
	v_mul_f32_e32 v155, v159, v159
	v_mul_f32_e32 v159, v193, v193
	v_cndmask_b32_e64 v152, v188, v152, s[2:3]
	v_cmp_lt_i32_e64 s[2:3], v154, v153
	v_fmac_f32_e32 v155, v158, v158
	v_fmac_f32_e32 v159, v192, v192
	v_cndmask_b32_e64 v153, v188, v154, s[2:3]
	v_mul_f32_e32 v154, v157, v157
	v_mul_f32_e32 v157, v191, v191
	v_fmac_f32_e32 v154, v156, v156
	v_fmac_f32_e32 v157, v190, v190
	v_add_f32_e32 v154, v154, v155
	v_add_f32_e32 v155, v157, v159
	v_add_f32_e32 v156, v154, v155
	v_lshlrev_b32_e32 v152, 2, v152
	s_waitcnt vmcnt(1)
	v_pk_fma_f32 v[150:151], v[150:151], v[110:111], v[196:197]
	v_pk_fma_f32 v[148:149], v[148:149], v[108:109], v[194:195]
	s_waitcnt vmcnt(0)
	v_pk_fma_f32 v[146:147], v[146:147], v[106:107], v[200:201]
	v_pk_fma_f32 v[144:145], v[144:145], v[104:105], v[198:199]
	v_mul_f32_e32 v157, v149, v149
	v_mul_f32_e32 v158, v151, v151
	v_mul_f32_e32 v159, v145, v145
	v_mul_f32_e32 v189, v147, v147
	v_fmac_f32_e32 v157, v148, v148
	v_fmac_f32_e32 v158, v150, v150
	v_fmac_f32_e32 v159, v144, v144
	v_fmac_f32_e32 v189, v146, v146
	global_store_dwordx4 v[202:203], v[148:151], off offset:512
	global_store_dwordx4 v[202:203], v[144:147], off offset:528
	v_pk_mul_f32 v[154:155], v[78:79], v[150:151]
	v_add_f32_e32 v150, v157, v158
	v_add_f32_e32 v151, v159, v189
	v_add_f32_e32 v150, v150, v151
	v_add_f32_e32 v158, v156, v150
	ds_bpermute_b32 v159, v152, v158
	v_pk_mul_f32 v[156:157], v[86:87], v[146:147]
	v_pk_mul_f32 v[150:151], v[84:85], v[144:145]
	v_lshlrev_b32_e32 v146, 2, v153
	v_pk_mul_f32 v[148:149], v[76:77], v[148:149]
	s_waitcnt lgkmcnt(0)
	v_add_f32_e32 v144, v158, v159
	ds_bpermute_b32 v145, v146, v144
	v_cvt_pk_bf16_f32 v148, v148, v149
	v_cvt_pk_bf16_f32 v149, v154, v155
	v_cvt_pk_bf16_f32 v150, v150, v151
	v_cvt_pk_bf16_f32 v151, v156, v157
	global_store_dwordx4 v[204:205], v[148:151], off offset:256
	s_and_saveexec_b64 s[2:3], vcc
	s_cbranch_execz .LBB0_2034
	v_lshl_add_u64 v[148:149], v[182:183], 2, s[12:13]
	s_waitcnt lgkmcnt(0)
	v_add_f32_e32 v144, v144, v145
	v_mov_b32_e32 v228, v144
	v_mov_b32_e32 v236, v148
	v_mov_b32_e32 v237, v149
.LBB0_2034:
	s_or_b64 exec, exec, s[2:3]
	v_add_u32_e32 v144, 16, v182
	s_waitcnt lgkmcnt(0)
	v_ashrrev_i32_e32 v145, 31, v144
	v_lshlrev_b64 v[148:149], 13, v[144:145]
	v_lshl_add_u64 v[148:149], s[90:91], 0, v[148:149]
	v_lshl_add_u64 v[158:159], v[180:181], 2, v[148:149]
	global_load_dwordx4 v[148:151], v[158:159], off
	global_load_dwordx4 v[154:157], v[158:159], off offset:16
	v_lshlrev_b64 v[190:191], 12, v[144:145]
	v_lshl_add_u64 v[190:191], s[38:39], 0, v[190:191]
	v_lshl_add_u64 v[190:191], v[180:181], 1, v[190:191]
	s_waitcnt vmcnt(1)
	v_pk_fma_f32 v[142:143], v[142:143], v[74:75], v[150:151]
	v_pk_fma_f32 v[140:141], v[140:141], v[72:73], v[148:149]
	s_waitcnt vmcnt(0)
	v_pk_fma_f32 v[138:139], v[138:139], v[102:103], v[156:157]
	v_pk_fma_f32 v[136:137], v[136:137], v[100:101], v[154:155]
	v_pk_mul_f32 v[150:151], v[98:99], v[142:143]
	v_pk_mul_f32 v[148:149], v[96:97], v[140:141]
	global_store_dwordx4 v[158:159], v[140:143], off
	global_store_dwordx4 v[158:159], v[136:139], off offset:16
	v_pk_mul_f32 v[154:155], v[94:95], v[138:139]
	v_pk_mul_f32 v[156:157], v[92:93], v[136:137]
	v_cvt_pk_bf16_f32 v148, v148, v149
	v_cvt_pk_bf16_f32 v149, v150, v151
	v_mul_f32_e32 v141, v141, v141
	v_cvt_pk_bf16_f32 v150, v156, v157
	v_cvt_pk_bf16_f32 v151, v154, v155
	global_store_dwordx4 v[190:191], v[148:151], off
	global_load_dwordx4 v[148:151], v[158:159], off offset:512
	s_nop 0
	global_load_dwordx4 v[154:157], v[158:159], off offset:528
	v_mul_f32_e32 v143, v143, v143
	v_mul_f32_e32 v137, v137, v137
	v_mul_f32_e32 v139, v139, v139
	v_fmac_f32_e32 v141, v140, v140
	v_fmac_f32_e32 v143, v142, v142
	v_fmac_f32_e32 v137, v136, v136
	v_fmac_f32_e32 v139, v138, v138
	v_add_f32_e32 v136, v141, v143
	v_add_f32_e32 v137, v137, v139
	v_add_f32_e32 v136, v136, v137
	s_waitcnt vmcnt(1)
	v_pk_fma_f32 v[134:135], v[134:135], v[110:111], v[150:151]
	v_pk_fma_f32 v[132:133], v[132:133], v[108:109], v[148:149]
	s_waitcnt vmcnt(0)
	v_pk_fma_f32 v[130:131], v[130:131], v[106:107], v[156:157]
	v_pk_fma_f32 v[128:129], v[128:129], v[104:105], v[154:155]
	v_mul_f32_e32 v137, v133, v133
	v_mul_f32_e32 v138, v135, v135
	v_mul_f32_e32 v139, v129, v129
	v_mul_f32_e32 v140, v131, v131
	v_fmac_f32_e32 v137, v132, v132
	v_fmac_f32_e32 v138, v134, v134
	v_fmac_f32_e32 v139, v128, v128
	v_fmac_f32_e32 v140, v130, v130
	v_add_f32_e32 v137, v137, v138
	v_add_f32_e32 v138, v139, v140
	v_add_f32_e32 v137, v137, v138
	v_add_f32_e32 v140, v136, v137
	ds_bpermute_b32 v141, v152, v140
	global_store_dwordx4 v[158:159], v[132:135], off offset:512
	global_store_dwordx4 v[158:159], v[128:131], off offset:528
	v_pk_mul_f32 v[138:139], v[84:85], v[128:129]
	v_pk_mul_f32 v[132:133], v[76:77], v[132:133]
	v_pk_mul_f32 v[134:135], v[78:79], v[134:135]
	s_waitcnt lgkmcnt(0)
	v_add_f32_e32 v128, v140, v141
	ds_bpermute_b32 v129, v146, v128
	v_pk_mul_f32 v[136:137], v[86:87], v[130:131]
	v_cvt_pk_bf16_f32 v130, v132, v133
	v_cvt_pk_bf16_f32 v131, v134, v135
	v_cvt_pk_bf16_f32 v132, v138, v139
	s_nop 0
	v_cvt_pk_bf16_f32 v133, v136, v137
	global_store_dwordx4 v[190:191], v[130:133], off offset:256
	s_and_saveexec_b64 s[2:3], vcc
	s_cbranch_execz .LBB0_2036
	v_lshl_add_u64 v[130:131], v[144:145], 2, s[12:13]
	s_waitcnt lgkmcnt(0)
	v_add_f32_e32 v128, v128, v129
	v_mov_b32_e32 v229, v128
.LBB0_2036:
	s_or_b64 exec, exec, s[2:3]
	v_add_u32_e32 v128, 32, v182
	s_waitcnt lgkmcnt(0)
	v_ashrrev_i32_e32 v129, 31, v128
	v_lshlrev_b64 v[130:131], 13, v[128:129]
	v_lshl_add_u64 v[130:131], s[90:91], 0, v[130:131]
	v_lshl_add_u64 v[138:139], v[180:181], 2, v[130:131]
	global_load_dwordx4 v[130:133], v[138:139], off
	global_load_dwordx4 v[134:137], v[138:139], off offset:16
	v_lshlrev_b64 v[140:141], 12, v[128:129]
	v_lshl_add_u64 v[140:141], s[38:39], 0, v[140:141]
	v_lshl_add_u64 v[140:141], v[180:181], 1, v[140:141]
	s_waitcnt vmcnt(1)
	v_pk_fma_f32 v[126:127], v[126:127], v[74:75], v[132:133]
	v_pk_fma_f32 v[124:125], v[124:125], v[72:73], v[130:131]
	s_waitcnt vmcnt(0)
	v_pk_fma_f32 v[122:123], v[122:123], v[102:103], v[136:137]
	v_pk_fma_f32 v[120:121], v[120:121], v[100:101], v[134:135]
	v_pk_mul_f32 v[132:133], v[98:99], v[126:127]
	v_pk_mul_f32 v[130:131], v[96:97], v[124:125]
	global_store_dwordx4 v[138:139], v[124:127], off
	global_store_dwordx4 v[138:139], v[120:123], off offset:16
	v_pk_mul_f32 v[134:135], v[94:95], v[122:123]
	v_pk_mul_f32 v[136:137], v[92:93], v[120:121]
	v_cvt_pk_bf16_f32 v130, v130, v131
	v_cvt_pk_bf16_f32 v131, v132, v133
	v_mul_f32_e32 v125, v125, v125
	v_cvt_pk_bf16_f32 v132, v136, v137
	v_cvt_pk_bf16_f32 v133, v134, v135
	global_store_dwordx4 v[140:141], v[130:133], off
	global_load_dwordx4 v[130:133], v[138:139], off offset:512
	s_nop 0
	global_load_dwordx4 v[134:137], v[138:139], off offset:528
	v_mul_f32_e32 v127, v127, v127
	v_mul_f32_e32 v121, v121, v121
	v_mul_f32_e32 v123, v123, v123
	v_fmac_f32_e32 v125, v124, v124
	v_fmac_f32_e32 v127, v126, v126
	v_fmac_f32_e32 v121, v120, v120
	v_fmac_f32_e32 v123, v122, v122
	v_add_f32_e32 v120, v125, v127
	v_add_f32_e32 v121, v121, v123
	v_add_f32_e32 v120, v120, v121
	s_waitcnt vmcnt(1)
	v_pk_fma_f32 v[118:119], v[118:119], v[110:111], v[132:133]
	v_pk_fma_f32 v[116:117], v[116:117], v[108:109], v[130:131]
	s_waitcnt vmcnt(0)
	v_pk_fma_f32 v[114:115], v[114:115], v[106:107], v[136:137]
	v_pk_fma_f32 v[112:113], v[112:113], v[104:105], v[134:135]
	v_mul_f32_e32 v121, v117, v117
	v_mul_f32_e32 v122, v119, v119
	v_mul_f32_e32 v123, v113, v113
	v_mul_f32_e32 v124, v115, v115
	v_fmac_f32_e32 v121, v116, v116
	v_fmac_f32_e32 v122, v118, v118
	v_fmac_f32_e32 v123, v112, v112
	v_fmac_f32_e32 v124, v114, v114
	v_add_f32_e32 v121, v121, v122
	v_add_f32_e32 v122, v123, v124
	v_add_f32_e32 v121, v121, v122
	v_add_f32_e32 v124, v120, v121
	ds_bpermute_b32 v125, v152, v124
	global_store_dwordx4 v[138:139], v[116:119], off offset:512
	global_store_dwordx4 v[138:139], v[112:115], off offset:528
	v_pk_mul_f32 v[122:123], v[84:85], v[112:113]
	v_pk_mul_f32 v[116:117], v[76:77], v[116:117]
	v_pk_mul_f32 v[118:119], v[78:79], v[118:119]
	s_waitcnt lgkmcnt(0)
	v_add_f32_e32 v112, v124, v125
	ds_bpermute_b32 v113, v146, v112
	v_pk_mul_f32 v[120:121], v[86:87], v[114:115]
	v_cvt_pk_bf16_f32 v114, v116, v117
	v_cvt_pk_bf16_f32 v115, v118, v119
	v_cvt_pk_bf16_f32 v116, v122, v123
	s_nop 0
	v_cvt_pk_bf16_f32 v117, v120, v121
	global_store_dwordx4 v[140:141], v[114:117], off offset:256
	s_and_saveexec_b64 s[2:3], vcc
	s_cbranch_execz .LBB0_2038
	v_lshl_add_u64 v[114:115], v[128:129], 2, s[12:13]
	s_waitcnt lgkmcnt(0)
	v_add_f32_e32 v112, v112, v113
	v_mov_b32_e32 v230, v112
.LBB0_2038:
	s_or_b64 exec, exec, s[2:3]
	v_add_u32_e32 v112, 48, v182
	s_waitcnt lgkmcnt(0)
	v_ashrrev_i32_e32 v113, 31, v112
	v_lshlrev_b64 v[114:115], 13, v[112:113]
	v_lshl_add_u64 v[114:115], s[90:91], 0, v[114:115]
	v_lshl_add_u64 v[122:123], v[180:181], 2, v[114:115]
	global_load_dwordx4 v[114:117], v[122:123], off
	global_load_dwordx4 v[118:121], v[122:123], off offset:16
	v_lshlrev_b64 v[124:125], 12, v[112:113]
	v_lshl_add_u64 v[124:125], s[38:39], 0, v[124:125]
	v_lshl_add_u64 v[124:125], v[180:181], 1, v[124:125]
	s_waitcnt vmcnt(1)
	v_pk_fma_f32 v[90:91], v[90:91], v[74:75], v[116:117]
	v_pk_fma_f32 v[88:89], v[88:89], v[72:73], v[114:115]
	s_waitcnt vmcnt(0)
	v_pk_fma_f32 v[82:83], v[82:83], v[102:103], v[120:121]
	v_pk_fma_f32 v[80:81], v[80:81], v[100:101], v[118:119]
	v_pk_mul_f32 v[116:117], v[98:99], v[90:91]
	v_pk_mul_f32 v[114:115], v[96:97], v[88:89]
	global_store_dwordx4 v[122:123], v[88:91], off
	global_store_dwordx4 v[122:123], v[80:83], off offset:16
	v_pk_mul_f32 v[118:119], v[94:95], v[82:83]
	v_pk_mul_f32 v[120:121], v[92:93], v[80:81]
	v_cvt_pk_bf16_f32 v114, v114, v115
	v_cvt_pk_bf16_f32 v115, v116, v117
	v_mul_f32_e32 v89, v89, v89
	v_cvt_pk_bf16_f32 v116, v120, v121
	v_cvt_pk_bf16_f32 v117, v118, v119
	global_store_dwordx4 v[124:125], v[114:117], off
	global_load_dwordx4 v[114:117], v[122:123], off offset:512
	s_nop 0
	global_load_dwordx4 v[118:121], v[122:123], off offset:528
	v_mul_f32_e32 v91, v91, v91
	v_mul_f32_e32 v81, v81, v81
	v_mul_f32_e32 v83, v83, v83
	v_fmac_f32_e32 v89, v88, v88
	v_fmac_f32_e32 v91, v90, v90
	v_fmac_f32_e32 v81, v80, v80
	v_fmac_f32_e32 v83, v82, v82
	v_add_f32_e32 v80, v89, v91
	v_add_f32_e32 v81, v81, v83
	v_add_f32_e32 v80, v80, v81
	s_waitcnt vmcnt(1)
	v_pk_fma_f32 v[70:71], v[70:71], v[110:111], v[116:117]
	v_pk_fma_f32 v[68:69], v[68:69], v[108:109], v[114:115]
	s_waitcnt vmcnt(0)
	v_pk_fma_f32 v[66:67], v[66:67], v[106:107], v[120:121]
	v_pk_fma_f32 v[64:65], v[64:65], v[104:105], v[118:119]
	v_mul_f32_e32 v81, v69, v69
	v_mul_f32_e32 v82, v71, v71
	v_mul_f32_e32 v83, v65, v65
	v_mul_f32_e32 v88, v67, v67
	v_fmac_f32_e32 v81, v68, v68
	v_fmac_f32_e32 v82, v70, v70
	v_fmac_f32_e32 v83, v64, v64
	v_fmac_f32_e32 v88, v66, v66
	v_add_f32_e32 v81, v81, v82
	v_add_f32_e32 v82, v83, v88
	v_add_f32_e32 v81, v81, v82
	v_add_f32_e32 v88, v80, v81
	ds_bpermute_b32 v89, v152, v88
	global_store_dwordx4 v[122:123], v[68:71], off offset:512
	global_store_dwordx4 v[122:123], v[64:67], off offset:528
	v_pk_mul_f32 v[82:83], v[84:85], v[64:65]
	v_pk_mul_f32 v[68:69], v[76:77], v[68:69]
	v_pk_mul_f32 v[70:71], v[78:79], v[70:71]
	s_waitcnt lgkmcnt(0)
	v_add_f32_e32 v64, v88, v89
	ds_bpermute_b32 v65, v146, v64
	v_pk_mul_f32 v[80:81], v[86:87], v[66:67]
	v_cvt_pk_bf16_f32 v66, v68, v69
	v_cvt_pk_bf16_f32 v67, v70, v71
	v_cvt_pk_bf16_f32 v68, v82, v83
	s_nop 0
	v_cvt_pk_bf16_f32 v69, v80, v81
	global_store_dwordx4 v[124:125], v[66:69], off offset:256
	s_and_saveexec_b64 s[2:3], vcc
	s_cbranch_execz .LBB0_2040
	v_lshl_add_u64 v[66:67], v[112:113], 2, s[12:13]
	s_waitcnt lgkmcnt(0)
	v_add_f32_e32 v64, v64, v65
	v_mov_b32_e32 v231, v64
.LBB0_2040:
	s_or_b64 exec, exec, s[2:3]
	v_add_u32_e32 v64, 0x80, v182
	s_waitcnt lgkmcnt(0)
	v_ashrrev_i32_e32 v65, 31, v64
	v_lshlrev_b64 v[66:67], 13, v[64:65]
	v_lshl_add_u64 v[66:67], s[90:91], 0, v[66:67]
	v_lshl_add_u64 v[70:71], v[180:181], 2, v[66:67]
	global_load_dwordx4 v[66:69], v[70:71], off
	global_load_dwordx4 v[80:83], v[70:71], off offset:16
	v_lshlrev_b64 v[88:89], 12, v[64:65]
	v_lshl_add_u64 v[88:89], s[38:39], 0, v[88:89]
	v_lshl_add_u64 v[88:89], v[180:181], 1, v[88:89]
	s_waitcnt vmcnt(1)
	v_pk_fma_f32 v[62:63], v[62:63], v[74:75], v[68:69]
	v_pk_fma_f32 v[60:61], v[60:61], v[72:73], v[66:67]
	s_waitcnt vmcnt(0)
	v_pk_fma_f32 v[58:59], v[58:59], v[102:103], v[82:83]
	v_pk_fma_f32 v[56:57], v[56:57], v[100:101], v[80:81]
	v_pk_mul_f32 v[68:69], v[98:99], v[62:63]
	v_pk_mul_f32 v[66:67], v[96:97], v[60:61]
	global_store_dwordx4 v[70:71], v[60:63], off
	global_store_dwordx4 v[70:71], v[56:59], off offset:16
	v_pk_mul_f32 v[80:81], v[94:95], v[58:59]
	v_pk_mul_f32 v[82:83], v[92:93], v[56:57]
	v_cvt_pk_bf16_f32 v66, v66, v67
	v_cvt_pk_bf16_f32 v67, v68, v69
	v_mul_f32_e32 v61, v61, v61
	v_cvt_pk_bf16_f32 v68, v82, v83
	v_cvt_pk_bf16_f32 v69, v80, v81
	global_store_dwordx4 v[88:89], v[66:69], off
	global_load_dwordx4 v[66:69], v[70:71], off offset:512
	s_nop 0
	global_load_dwordx4 v[80:83], v[70:71], off offset:528
	v_mul_f32_e32 v63, v63, v63
	v_mul_f32_e32 v57, v57, v57
	v_mul_f32_e32 v59, v59, v59
	v_fmac_f32_e32 v61, v60, v60
	v_fmac_f32_e32 v63, v62, v62
	v_fmac_f32_e32 v57, v56, v56
	v_fmac_f32_e32 v59, v58, v58
	v_add_f32_e32 v56, v61, v63
	v_add_f32_e32 v57, v57, v59
	v_add_f32_e32 v56, v56, v57
	s_waitcnt vmcnt(1)
	v_pk_fma_f32 v[54:55], v[54:55], v[110:111], v[68:69]
	v_pk_fma_f32 v[52:53], v[52:53], v[108:109], v[66:67]
	s_waitcnt vmcnt(0)
	v_pk_fma_f32 v[50:51], v[50:51], v[106:107], v[82:83]
	v_pk_fma_f32 v[48:49], v[48:49], v[104:105], v[80:81]
	v_mul_f32_e32 v57, v53, v53
	v_mul_f32_e32 v58, v55, v55
	v_mul_f32_e32 v59, v49, v49
	v_mul_f32_e32 v60, v51, v51
	v_fmac_f32_e32 v57, v52, v52
	v_fmac_f32_e32 v58, v54, v54
	v_fmac_f32_e32 v59, v48, v48
	v_fmac_f32_e32 v60, v50, v50
	v_add_f32_e32 v57, v57, v58
	v_add_f32_e32 v58, v59, v60
	v_add_f32_e32 v57, v57, v58
	v_add_f32_e32 v60, v56, v57
	ds_bpermute_b32 v61, v152, v60
	global_store_dwordx4 v[70:71], v[52:55], off offset:512
	global_store_dwordx4 v[70:71], v[48:51], off offset:528
	v_pk_mul_f32 v[58:59], v[84:85], v[48:49]
	v_pk_mul_f32 v[52:53], v[76:77], v[52:53]
	v_pk_mul_f32 v[54:55], v[78:79], v[54:55]
	s_waitcnt lgkmcnt(0)
	v_add_f32_e32 v48, v60, v61
	ds_bpermute_b32 v49, v146, v48
	v_pk_mul_f32 v[56:57], v[86:87], v[50:51]
	v_cvt_pk_bf16_f32 v50, v52, v53
	v_cvt_pk_bf16_f32 v51, v54, v55
	v_cvt_pk_bf16_f32 v52, v58, v59
	s_nop 0
	v_cvt_pk_bf16_f32 v53, v56, v57
	global_store_dwordx4 v[88:89], v[50:53], off offset:256
	s_and_saveexec_b64 s[2:3], vcc
	s_cbranch_execz .LBB0_2042
	v_lshl_add_u64 v[50:51], v[64:65], 2, s[12:13]
	s_waitcnt lgkmcnt(0)
	v_add_f32_e32 v48, v48, v49
	v_mov_b32_e32 v232, v48
.LBB0_2042:
	s_or_b64 exec, exec, s[2:3]
	v_add_u32_e32 v48, 0x90, v182
	s_waitcnt lgkmcnt(0)
	v_ashrrev_i32_e32 v49, 31, v48
	v_lshlrev_b64 v[50:51], 13, v[48:49]
	v_lshl_add_u64 v[50:51], s[90:91], 0, v[50:51]
	v_lshl_add_u64 v[58:59], v[180:181], 2, v[50:51]
	global_load_dwordx4 v[50:53], v[58:59], off
	global_load_dwordx4 v[54:57], v[58:59], off offset:16
	v_lshlrev_b64 v[60:61], 12, v[48:49]
	v_lshl_add_u64 v[60:61], s[38:39], 0, v[60:61]
	v_lshl_add_u64 v[60:61], v[180:181], 1, v[60:61]
	s_waitcnt vmcnt(1)
	v_pk_fma_f32 v[46:47], v[46:47], v[74:75], v[52:53]
	v_pk_fma_f32 v[44:45], v[44:45], v[72:73], v[50:51]
	s_waitcnt vmcnt(0)
	v_pk_fma_f32 v[42:43], v[42:43], v[102:103], v[56:57]
	v_pk_fma_f32 v[40:41], v[40:41], v[100:101], v[54:55]
	v_pk_mul_f32 v[52:53], v[98:99], v[46:47]
	v_pk_mul_f32 v[50:51], v[96:97], v[44:45]
	global_store_dwordx4 v[58:59], v[44:47], off
	global_store_dwordx4 v[58:59], v[40:43], off offset:16
	v_pk_mul_f32 v[54:55], v[94:95], v[42:43]
	v_pk_mul_f32 v[56:57], v[92:93], v[40:41]
	v_cvt_pk_bf16_f32 v50, v50, v51
	v_cvt_pk_bf16_f32 v51, v52, v53
	v_mul_f32_e32 v45, v45, v45
	v_cvt_pk_bf16_f32 v52, v56, v57
	v_cvt_pk_bf16_f32 v53, v54, v55
	global_store_dwordx4 v[60:61], v[50:53], off
	global_load_dwordx4 v[50:53], v[58:59], off offset:512
	s_nop 0
	global_load_dwordx4 v[54:57], v[58:59], off offset:528
	v_mul_f32_e32 v47, v47, v47
	v_mul_f32_e32 v41, v41, v41
	v_mul_f32_e32 v43, v43, v43
	v_fmac_f32_e32 v45, v44, v44
	v_fmac_f32_e32 v47, v46, v46
	v_fmac_f32_e32 v41, v40, v40
	v_fmac_f32_e32 v43, v42, v42
	v_add_f32_e32 v40, v45, v47
	v_add_f32_e32 v41, v41, v43
	v_add_f32_e32 v40, v40, v41
	s_waitcnt vmcnt(1)
	v_pk_fma_f32 v[38:39], v[38:39], v[110:111], v[52:53]
	v_pk_fma_f32 v[36:37], v[36:37], v[108:109], v[50:51]
	s_waitcnt vmcnt(0)
	v_pk_fma_f32 v[34:35], v[34:35], v[106:107], v[56:57]
	v_pk_fma_f32 v[32:33], v[32:33], v[104:105], v[54:55]
	v_mul_f32_e32 v41, v37, v37
	v_mul_f32_e32 v42, v39, v39
	v_mul_f32_e32 v43, v33, v33
	v_mul_f32_e32 v44, v35, v35
	v_fmac_f32_e32 v41, v36, v36
	v_fmac_f32_e32 v42, v38, v38
	v_fmac_f32_e32 v43, v32, v32
	v_fmac_f32_e32 v44, v34, v34
	v_add_f32_e32 v41, v41, v42
	v_add_f32_e32 v42, v43, v44
	v_add_f32_e32 v41, v41, v42
	v_add_f32_e32 v44, v40, v41
	ds_bpermute_b32 v45, v152, v44
	global_store_dwordx4 v[58:59], v[36:39], off offset:512
	global_store_dwordx4 v[58:59], v[32:35], off offset:528
	v_pk_mul_f32 v[42:43], v[84:85], v[32:33]
	v_pk_mul_f32 v[36:37], v[76:77], v[36:37]
	v_pk_mul_f32 v[38:39], v[78:79], v[38:39]
	s_waitcnt lgkmcnt(0)
	v_add_f32_e32 v32, v44, v45
	ds_bpermute_b32 v33, v146, v32
	v_pk_mul_f32 v[40:41], v[86:87], v[34:35]
	v_cvt_pk_bf16_f32 v34, v36, v37
	v_cvt_pk_bf16_f32 v35, v38, v39
	v_cvt_pk_bf16_f32 v36, v42, v43
	s_nop 0
	v_cvt_pk_bf16_f32 v37, v40, v41
	global_store_dwordx4 v[60:61], v[34:37], off offset:256
	s_and_saveexec_b64 s[2:3], vcc
	s_cbranch_execz .LBB0_2044
	v_lshl_add_u64 v[34:35], v[48:49], 2, s[12:13]
	s_waitcnt lgkmcnt(0)
	v_add_f32_e32 v32, v32, v33
	v_mov_b32_e32 v233, v32
.LBB0_2044:
	s_or_b64 exec, exec, s[2:3]
	v_add_u32_e32 v32, 0xa0, v182
	s_waitcnt lgkmcnt(0)
	v_ashrrev_i32_e32 v33, 31, v32
	v_lshlrev_b64 v[34:35], 13, v[32:33]
	v_lshl_add_u64 v[34:35], s[90:91], 0, v[34:35]
	v_lshl_add_u64 v[42:43], v[180:181], 2, v[34:35]
	global_load_dwordx4 v[34:37], v[42:43], off
	global_load_dwordx4 v[38:41], v[42:43], off offset:16
	v_lshlrev_b64 v[44:45], 12, v[32:33]
	v_lshl_add_u64 v[44:45], s[38:39], 0, v[44:45]
	v_lshl_add_u64 v[44:45], v[180:181], 1, v[44:45]
	s_waitcnt vmcnt(1)
	v_pk_fma_f32 v[30:31], v[30:31], v[74:75], v[36:37]
	v_pk_fma_f32 v[28:29], v[28:29], v[72:73], v[34:35]
	s_waitcnt vmcnt(0)
	v_pk_fma_f32 v[26:27], v[26:27], v[102:103], v[40:41]
	v_pk_fma_f32 v[24:25], v[24:25], v[100:101], v[38:39]
	v_pk_mul_f32 v[36:37], v[98:99], v[30:31]
	v_pk_mul_f32 v[34:35], v[96:97], v[28:29]
	global_store_dwordx4 v[42:43], v[28:31], off
	global_store_dwordx4 v[42:43], v[24:27], off offset:16
	v_pk_mul_f32 v[38:39], v[94:95], v[26:27]
	v_pk_mul_f32 v[40:41], v[92:93], v[24:25]
	v_cvt_pk_bf16_f32 v34, v34, v35
	v_cvt_pk_bf16_f32 v35, v36, v37
	v_mul_f32_e32 v29, v29, v29
	v_cvt_pk_bf16_f32 v36, v40, v41
	v_cvt_pk_bf16_f32 v37, v38, v39
	global_store_dwordx4 v[44:45], v[34:37], off
	global_load_dwordx4 v[34:37], v[42:43], off offset:512
	s_nop 0
	global_load_dwordx4 v[38:41], v[42:43], off offset:528
	v_mul_f32_e32 v31, v31, v31
	v_mul_f32_e32 v25, v25, v25
	v_mul_f32_e32 v27, v27, v27
	v_fmac_f32_e32 v29, v28, v28
	v_fmac_f32_e32 v31, v30, v30
	v_fmac_f32_e32 v25, v24, v24
	v_fmac_f32_e32 v27, v26, v26
	v_add_f32_e32 v24, v29, v31
	v_add_f32_e32 v25, v25, v27
	v_add_f32_e32 v24, v24, v25
	s_waitcnt vmcnt(1)
	v_pk_fma_f32 v[22:23], v[22:23], v[110:111], v[36:37]
	v_pk_fma_f32 v[20:21], v[20:21], v[108:109], v[34:35]
	s_waitcnt vmcnt(0)
	v_pk_fma_f32 v[18:19], v[18:19], v[106:107], v[40:41]
	v_pk_fma_f32 v[16:17], v[16:17], v[104:105], v[38:39]
	v_mul_f32_e32 v25, v21, v21
	v_mul_f32_e32 v26, v23, v23
	v_mul_f32_e32 v27, v17, v17
	v_mul_f32_e32 v28, v19, v19
	v_fmac_f32_e32 v25, v20, v20
	v_fmac_f32_e32 v26, v22, v22
	v_fmac_f32_e32 v27, v16, v16
	v_fmac_f32_e32 v28, v18, v18
	v_add_f32_e32 v25, v25, v26
	v_add_f32_e32 v26, v27, v28
	v_add_f32_e32 v25, v25, v26
	v_add_f32_e32 v28, v24, v25
	ds_bpermute_b32 v29, v152, v28
	global_store_dwordx4 v[42:43], v[20:23], off offset:512
	global_store_dwordx4 v[42:43], v[16:19], off offset:528
	v_pk_mul_f32 v[26:27], v[84:85], v[16:17]
	v_pk_mul_f32 v[20:21], v[76:77], v[20:21]
	v_pk_mul_f32 v[22:23], v[78:79], v[22:23]
	s_waitcnt lgkmcnt(0)
	v_add_f32_e32 v16, v28, v29
	ds_bpermute_b32 v17, v146, v16
	v_pk_mul_f32 v[24:25], v[86:87], v[18:19]
	v_cvt_pk_bf16_f32 v18, v20, v21
	v_cvt_pk_bf16_f32 v19, v22, v23
	v_cvt_pk_bf16_f32 v20, v26, v27
	s_nop 0
	v_cvt_pk_bf16_f32 v21, v24, v25
	global_store_dwordx4 v[44:45], v[18:21], off offset:256
	s_and_saveexec_b64 s[2:3], vcc
	s_cbranch_execz .LBB0_2046
	v_lshl_add_u64 v[18:19], v[32:33], 2, s[12:13]
	s_waitcnt lgkmcnt(0)
	v_add_f32_e32 v16, v16, v17
	v_mov_b32_e32 v234, v16
.LBB0_2046:
	s_or_b64 exec, exec, s[2:3]
	v_add_u32_e32 v16, 0xb0, v182
	s_waitcnt lgkmcnt(0)
	v_ashrrev_i32_e32 v17, 31, v16
	v_lshlrev_b64 v[18:19], 13, v[16:17]
	v_lshl_add_u64 v[18:19], s[90:91], 0, v[18:19]
	v_lshl_add_u64 v[26:27], v[180:181], 2, v[18:19]
	global_load_dwordx4 v[18:21], v[26:27], off
	global_load_dwordx4 v[22:25], v[26:27], off offset:16
	v_lshlrev_b64 v[28:29], 12, v[16:17]
	v_lshl_add_u64 v[28:29], s[38:39], 0, v[28:29]
	v_lshl_add_u64 v[28:29], v[180:181], 1, v[28:29]
	s_waitcnt vmcnt(1)
	v_pk_fma_f32 v[14:15], v[14:15], v[74:75], v[20:21]
	v_pk_fma_f32 v[12:13], v[12:13], v[72:73], v[18:19]
	s_waitcnt vmcnt(0)
	v_pk_fma_f32 v[10:11], v[10:11], v[102:103], v[24:25]
	v_pk_fma_f32 v[8:9], v[8:9], v[100:101], v[22:23]
	v_pk_mul_f32 v[20:21], v[98:99], v[14:15]
	v_pk_mul_f32 v[18:19], v[96:97], v[12:13]
	global_store_dwordx4 v[26:27], v[12:15], off
	global_store_dwordx4 v[26:27], v[8:11], off offset:16
	v_pk_mul_f32 v[22:23], v[94:95], v[10:11]
	v_pk_mul_f32 v[24:25], v[92:93], v[8:9]
	v_cvt_pk_bf16_f32 v18, v18, v19
	v_cvt_pk_bf16_f32 v19, v20, v21
	v_mul_f32_e32 v13, v13, v13
	v_cvt_pk_bf16_f32 v20, v24, v25
	v_cvt_pk_bf16_f32 v21, v22, v23
	global_store_dwordx4 v[28:29], v[18:21], off
	global_load_dwordx4 v[18:21], v[26:27], off offset:512
	s_nop 0
	global_load_dwordx4 v[22:25], v[26:27], off offset:528
	v_mul_f32_e32 v15, v15, v15
	v_mul_f32_e32 v9, v9, v9
	v_mul_f32_e32 v11, v11, v11
	v_fmac_f32_e32 v13, v12, v12
	v_fmac_f32_e32 v15, v14, v14
	v_fmac_f32_e32 v9, v8, v8
	v_fmac_f32_e32 v11, v10, v10
	v_add_f32_e32 v8, v13, v15
	v_add_f32_e32 v9, v9, v11
	v_add_f32_e32 v8, v8, v9
	s_waitcnt vmcnt(1)
	v_pk_fma_f32 v[6:7], v[6:7], v[110:111], v[20:21]
	v_pk_fma_f32 v[4:5], v[4:5], v[108:109], v[18:19]
	s_waitcnt vmcnt(0)
	v_pk_fma_f32 v[2:3], v[2:3], v[106:107], v[24:25]
	v_pk_fma_f32 v[0:1], v[0:1], v[104:105], v[22:23]
	v_mul_f32_e32 v9, v5, v5
	v_mul_f32_e32 v10, v7, v7
	v_mul_f32_e32 v11, v1, v1
	v_mul_f32_e32 v12, v3, v3
	v_fmac_f32_e32 v9, v4, v4
	v_fmac_f32_e32 v10, v6, v6
	v_fmac_f32_e32 v11, v0, v0
	v_fmac_f32_e32 v12, v2, v2
	v_add_f32_e32 v9, v9, v10
	v_add_f32_e32 v10, v11, v12
	v_add_f32_e32 v9, v9, v10
	v_add_f32_e32 v12, v8, v9
	ds_bpermute_b32 v13, v152, v12
	global_store_dwordx4 v[26:27], v[4:7], off offset:512
	global_store_dwordx4 v[26:27], v[0:3], off offset:528
	v_pk_mul_f32 v[10:11], v[84:85], v[0:1]
	v_pk_mul_f32 v[4:5], v[76:77], v[4:5]
	v_pk_mul_f32 v[6:7], v[78:79], v[6:7]
	s_waitcnt lgkmcnt(0)
	v_add_f32_e32 v0, v12, v13
	ds_bpermute_b32 v1, v146, v0
	v_pk_mul_f32 v[8:9], v[86:87], v[2:3]
	v_cvt_pk_bf16_f32 v2, v4, v5
	v_cvt_pk_bf16_f32 v3, v6, v7
	v_cvt_pk_bf16_f32 v4, v10, v11
	s_nop 0
	v_cvt_pk_bf16_f32 v5, v8, v9
	global_store_dwordx4 v[28:29], v[2:5], off offset:256
	s_and_saveexec_b64 s[2:3], vcc
	s_cbranch_execz .LBB0_2048
	v_lshl_add_u64 v[2:3], v[16:17], 2, s[12:13]
	s_waitcnt lgkmcnt(0)
	v_add_f32_e32 v0, v0, v1
	v_mov_b32_e32 v235, v0
.LBB0_2048:
	s_or_b64 exec, exec, s[2:3]
	s_and_saveexec_b64 s[2:3], vcc
	global_atomic_add_f32 v[236:237], v228, off
	global_atomic_add_f32 v[236:237], v229, off offset:64
	global_atomic_add_f32 v[236:237], v230, off offset:128
	global_atomic_add_f32 v[236:237], v231, off offset:192
	global_atomic_add_f32 v[236:237], v232, off offset:512
	global_atomic_add_f32 v[236:237], v233, off offset:576
	global_atomic_add_f32 v[236:237], v234, off offset:640
	global_atomic_add_f32 v[236:237], v235, off offset:704
	s_or_b64 exec, exec, s[2:3]
	s_andn2_b64 vcc, exec, s[0:1]
	s_mov_b64 s[0:1], -1
	s_cbranch_vccnz .LBB0_2025
	s_andn2_b64 vcc, exec, s[6:7]
	s_cbranch_vccnz .LBB0_2024
	s_barrier
	s_branch .LBB0_2024
